# attention loops: waves skip the QK^T and PV MFMAs and LDS reads of tiles that are fully masked for them
# speedup vs baseline: 1.0048x; 1.0048x over previous
; #define LAS __attribute__((address_space(3)))
; DI void finishSM(f32x16& p0, f32x16& p1, float alpha, float& l_reg, bf16x8& pa0, bf16x8& pa1, bf16x8& pa2, bf16x8& pa3) {
; #pragma unroll
;   for (int r = 0; r < 16; ++r) p1[r] = __builtin_amdgcn_exp2f(p1[r]);
;   float ps = 0;
; #pragma unroll
;   for (int r = 0; r < 16; ++r) ps += p0[r];
; #pragma unroll
;   for (int r = 0; r < 16; ++r) ps += p1[r];
;   { auto rr = __builtin_amdgcn_permlane32_swap(__float_as_uint(ps), __float_as_uint(ps), false, false);
;     ps = __uint_as_float(rr[0]) + __uint_as_float(rr[1]); }
;   l_reg = l_reg * alpha + ps;
;     ...
;   PK4(p0, 0, pa0); PK4(p0, 8, pa1); PK4(p1, 0, pa2); PK4(p1, 8, pa3);
;     ...
; }
; template <int NQ> DI void qkt(f32x16& p0, f32x16& p1, const LAS char* Ks, const LAS char* KRs, const bf16x8* qr, int r32, int hi) {
;   p0 = f32x16{}; p1 = f32x16{};
; #pragma unroll
;   for (int d0 = 0; d0 < 8; ++d0) { const int cb = (d0 * 16 + hi * 8) * 2;
;     const bf16x8 b0 = *(const LAS bf16x8*)(Ks + KSWZ(r32, cb));
;     const bf16x8 b1 = *(const LAS bf16x8*)(Ks + KSWZ(32 + r32, cb));
;     p0 = __builtin_amdgcn_mfma_f32_32x32x16_bf16(b0, qr[d0], p0, 0, 0, 0);
;     p1 = __builtin_amdgcn_mfma_f32_32x32x16_bf16(b1, qr[d0], p1, 0, 0, 0); }
.LBB0_282:
	s_add_i32 s18, s49, -3
	s_cmp_gt_i32 s34, s18
	s_cbranch_scc1 .Lqsbb_skip
	s_cmp_gt_i32 s18, s25
	s_cbranch_scc1 .Lqsbb_skip
	ds_read_b128 v[80:83], v222 offset:58880
	ds_read_b128 v[84:87], v222 offset:50176
	ds_read_b128 v[192:195], v222 offset:50208
	ds_read_b128 v[196:199], v222 offset:58912
	v_exp_f32_e32 v200, v64
	v_add_f32_e32 v64, 0, v177
	s_waitcnt lgkmcnt(2)
	v_mfma_f32_32x32x16_bf16 v[96:111], v[84:87], v[144:147], 0
	v_add_f32_e32 v64, v179, v64
	v_add_f32_e32 v64, v175, v64
	v_add_f32_e32 v64, v178, v64
	v_add_f32_e32 v64, v174, v64
	v_add_f32_e32 v64, v176, v64
	v_add_f32_e32 v64, v172, v64
	v_add_f32_e32 v64, v173, v64
	v_mfma_f32_32x32x16_bf16 v[80:95], v[80:83], v[144:147], 0
	v_add_f32_e32 v64, v169, v64
	v_add_f32_e32 v64, v171, v64
	v_add_f32_e32 v64, v168, v64
	v_add_f32_e32 v64, v170, v64
	v_exp_f32_e32 v78, v78
	v_add_f32_e32 v64, v165, v64
	v_exp_f32_e32 v79, v79
	s_waitcnt lgkmcnt(1)
	v_mfma_f32_32x32x16_bf16 v[96:111], v[192:195], v[140:143], v[96:111]
	v_add_f32_e32 v64, v167, v64
	v_exp_f32_e32 v76, v76
	v_add_f32_e32 v64, v164, v64
	v_exp_f32_e32 v77, v77
	v_add_f32_e32 v64, v166, v64
	v_exp_f32_e32 v74, v74
	v_add_f32_e32 v64, v78, v64
	s_waitcnt lgkmcnt(0)
	v_mfma_f32_32x32x16_bf16 v[80:95], v[196:199], v[140:143], v[80:95]
	ds_read_b128 v[192:195], v222 offset:50240
	ds_read_b128 v[196:199], v222 offset:58944
	v_exp_f32_e32 v75, v75
	v_add_f32_e32 v64, v79, v64
	v_add_f32_e32 v64, v76, v64
	v_add_f32_e32 v64, v77, v64
	v_add_f32_e32 v64, v74, v64
	v_add_f32_e32 v64, v75, v64
	s_waitcnt lgkmcnt(1)
	v_mfma_f32_32x32x16_bf16 v[96:111], v[192:195], v[136:139], v[96:111]
	v_exp_f32_e32 v201, v65
	s_waitcnt lgkmcnt(0)
	v_mfma_f32_32x32x16_bf16 v[80:95], v[196:199], v[136:139], v[80:95]
	ds_read_b128 v[192:195], v222 offset:50272
	ds_read_b128 v[196:199], v222 offset:58976
	s_waitcnt lgkmcnt(1)
	v_mfma_f32_32x32x16_bf16 v[96:111], v[192:195], v[132:135], v[96:111]
	s_waitcnt lgkmcnt(0)
	v_mfma_f32_32x32x16_bf16 v[80:95], v[196:199], v[132:135], v[80:95]
	ds_read_b128 v[192:195], v222 offset:50304
	ds_read_b128 v[196:199], v222 offset:59008
	s_waitcnt lgkmcnt(1)
	v_mfma_f32_32x32x16_bf16 v[96:111], v[192:195], v[128:131], v[96:111]
	s_waitcnt lgkmcnt(0)
	v_mfma_f32_32x32x16_bf16 v[80:95], v[196:199], v[128:131], v[80:95]
	ds_read_b128 v[192:195], v222 offset:50336
	ds_read_b128 v[196:199], v222 offset:59040
	s_waitcnt lgkmcnt(1)
	v_mfma_f32_32x32x16_bf16 v[96:111], v[192:195], v[124:127], v[96:111]
	s_waitcnt lgkmcnt(0)
	v_mfma_f32_32x32x16_bf16 v[80:95], v[196:199], v[124:127], v[80:95]
	ds_read_b128 v[192:195], v222 offset:50368
	ds_read_b128 v[196:199], v222 offset:59072
	s_waitcnt lgkmcnt(1)
	v_mfma_f32_32x32x16_bf16 v[96:111], v[192:195], v[120:123], v[96:111]
	s_waitcnt lgkmcnt(0)
	v_mfma_f32_32x32x16_bf16 v[80:95], v[196:199], v[120:123], v[80:95]
	ds_read_b128 v[192:195], v222 offset:50400
	ds_read_b128 v[196:199], v222 offset:59104
	s_waitcnt lgkmcnt(1)
	v_mfma_f32_32x32x16_bf16 v[96:111], v[192:195], v[116:119], v[96:111]
	v_exp_f32_e32 v192, v72
	v_exp_f32_e32 v193, v73
	v_exp_f32_e32 v194, v70
	v_exp_f32_e32 v195, v71
	v_add_f32_e32 v64, v192, v64
	v_add_f32_e32 v64, v193, v64
	v_add_f32_e32 v64, v194, v64
	s_waitcnt lgkmcnt(0)
	v_mfma_f32_32x32x16_bf16 v[80:95], v[196:199], v[116:119], v[80:95]
	v_exp_f32_e32 v196, v68
	v_exp_f32_e32 v197, v69
	v_exp_f32_e32 v198, v66
	v_exp_f32_e32 v199, v67
	v_add_f32_e32 v64, v195, v64
	v_add_f32_e32 v64, v196, v64
	v_add_f32_e32 v64, v197, v64
	v_add_f32_e32 v64, v198, v64
	v_add_f32_e32 v64, v199, v64
	v_add_f32_e32 v64, v200, v64
	v_add_f32_e32 v232, v201, v64
	v_mov_b32_e32 v233, v232
	v_cvt_pk_bf16_f32 v64, v177, v179
	v_cvt_pk_bf16_f32 v65, v175, v178
	v_cvt_pk_bf16_f32 v66, v174, v176
	v_cvt_pk_bf16_f32 v67, v172, v173
	v_cvt_pk_bf16_f32 v68, v169, v171
	v_cvt_pk_bf16_f32 v69, v168, v170
	v_cvt_pk_bf16_f32 v70, v165, v167
	v_cvt_pk_bf16_f32 v71, v164, v166
	v_cvt_pk_bf16_f32 v72, v78, v79
	v_cvt_pk_bf16_f32 v73, v76, v77
	v_cvt_pk_bf16_f32 v74, v74, v75
	v_cvt_pk_bf16_f32 v75, v192, v193
	v_cvt_pk_bf16_f32 v76, v194, v195
	v_cvt_pk_bf16_f32 v77, v196, v197
	v_cvt_pk_bf16_f32 v78, v198, v199
	v_cvt_pk_bf16_f32 v79, v200, v201
	s_nop 1
	v_permlane32_swap_b32_e32 v232, v233
	v_permlane32_swap_b32_e32 v64, v66
	v_permlane32_swap_b32_e32 v65, v67
	v_permlane32_swap_b32_e32 v68, v70
	v_permlane32_swap_b32_e32 v69, v71
	v_permlane32_swap_b32_e32 v72, v74
	v_permlane32_swap_b32_e32 v73, v75
	v_permlane32_swap_b32_e32 v76, v78
	v_permlane32_swap_b32_e32 v77, v79
; #define LAS __attribute__((address_space(3)))
; #define SBAR() __builtin_amdgcn_sched_barrier(0)
; template <int OFF> DI s16x4 tr_read(int vb) { s16x4 r; asm volatile("ds_read_b64_tr_b16 %0, %1 offset:%2" : "=&v"(r) : "v"(vb), "i"(OFF) : "memory"); return r; }
; template <bool BAND> DI void partialSM(f32x16& p0, f32x16& p1, float& m_reg, float& mn, float& alpha, bool masked, const LAS float* tb, float C) {
;   if (masked) {
; #pragma unroll
;     for (int r = 0; r < 16; ++r) { p0[r] = -1e30f; p1[r] = -1e30f; }
;   } else if (BAND) {
; #pragma unroll
;     for (int r = 0; r < 16; ++r) { const int ko = (r & 3) + 8 * (r >> 2); p0[r] = fmaf(p0[r], C, tb[ko]); }
;     SBAR();
; #pragma unroll
;     for (int r = 0; r < 16; ++r) { const int ko = (r & 3) + 8 * (r >> 2); p1[r] = fmaf(p1[r], C, tb[ko + 32]); }
; template <int D0> DI void pv_one(f32x16& od, int vb, bf16x8 pa0, bf16x8 pa1, bf16x8 pa2, bf16x8 pa3) {
;   const s16x4 l0 = tr_read<v_rd_off(D0, 0, 0)>(vb), h0 = tr_read<v_rd_off(D0, 0, 1)>(vb), l1 = tr_read<v_rd_off(D0, 1, 0)>(vb), h1 = tr_read<v_rd_off(D0, 1, 1)>(vb);
;   const s16x4 l2 = tr_read<v_rd_off(D0, 2, 0)>(vb), h2 = tr_read<v_rd_off(D0, 2, 1)>(vb), l3 = tr_read<v_rd_off(D0, 3, 0)>(vb), h3 = tr_read<v_rd_off(D0, 3, 1)>(vb);
;   asm volatile("s_waitcnt lgkmcnt(0)" ::: "memory"); SBAR();
;     ...
;   od = __builtin_amdgcn_mfma_f32_32x32x16_bf16(pa0, PK(l0, h0), od, 0, 0, 0);
;   od = __builtin_amdgcn_mfma_f32_32x32x16_bf16(pa1, PK(l1, h1), od, 0, 0, 0);
;   od = __builtin_amdgcn_mfma_f32_32x32x16_bf16(pa2, PK(l2, h2), od, 0, 0, 0);
;   od = __builtin_amdgcn_mfma_f32_32x32x16_bf16(pa3, PK(l3, h3), od, 0, 0, 0);
;     ...
; }
; DI void pv_d0(f32x16* o, int vb, bf16x8 pa0, bf16x8 pa1, bf16x8 pa2, bf16x8 pa3) {
;   pv_one<0>(o[0], vb, pa0, pa1, pa2, pa3); pv_one<1>(o[1], vb, pa0, pa1, pa2, pa3); pv_one<2>(o[2], vb, pa0, pa1, pa2, pa3); pv_one<3>(o[3], vb, pa0, pa1, pa2, pa3);
.Lqsbb_join:
	s_add_i32 s16, s49, -1
	s_min_i32 s16, s16, s35
	s_ashr_i32 s17, s16, 31
	s_lshl_b64 s[16:17], s[16:17], 18
	s_add_u32 s22, s12, s16
	s_addc_u32 s23, s13, s17
	s_add_u32 s16, s14, s16
	s_addc_u32 s17, s15, s17
	v_lshl_add_u64 v[164:165], s[16:17], 0, v[112:113]
	v_lshl_add_u64 v[168:169], s[16:17], 0, v[114:115]
	v_lshl_add_u64 v[172:173], s[22:23], 0, v[112:113]
	v_lshl_add_u64 v[176:177], s[22:23], 0, v[114:115]
	global_load_dwordx4 v[164:167], v[164:165], off
	s_nop 0
	global_load_dwordx4 v[168:171], v[168:169], off
	s_nop 0
	global_load_dwordx4 v[172:175], v[172:173], off
	s_nop 0
	global_load_dwordx4 v[176:179], v[176:177], off
	s_add_i32 vcc_lo, s18, -1
	s_cmp_gt_i32 s34, vcc_lo
	s_cbranch_scc1 .Lpvbb_skip
	s_cmp_gt_i32 vcc_lo, s25
	s_cbranch_scc1 .Lpvbb_skip
	ds_read_b64_tr_b16 v[192:193], v223 offset:0
	ds_read_b64_tr_b16 v[194:195], v223 offset:0x800
	ds_read_b64_tr_b16 v[196:197], v223 offset:0x1000
	ds_read_b64_tr_b16 v[198:199], v223 offset:0x1800
	ds_read_b64_tr_b16 v[200:201], v223 offset:0x2000
	ds_read_b64_tr_b16 v[202:203], v223 offset:0x2800
	ds_read_b64_tr_b16 v[204:205], v223 offset:0x3000
	ds_read_b64_tr_b16 v[206:207], v223 offset:0x3800
	s_waitcnt lgkmcnt(0)
	s_nop 0
	v_mfma_f32_32x32x16_bf16 v[48:63], v[64:67], v[192:195], v[48:63]
	ds_read_b64_tr_b16 v[192:193], v223 offset:0x200
	ds_read_b64_tr_b16 v[194:195], v223 offset:0xa00
	v_mfma_f32_32x32x16_bf16 v[48:63], v[68:71], v[196:199], v[48:63]
	ds_read_b64_tr_b16 v[196:197], v223 offset:0x1200
	ds_read_b64_tr_b16 v[198:199], v223 offset:0x1a00
	v_mfma_f32_32x32x16_bf16 v[48:63], v[72:75], v[200:203], v[48:63]
	ds_read_b64_tr_b16 v[200:201], v223 offset:0x2200
	ds_read_b64_tr_b16 v[202:203], v223 offset:0x2a00
	v_mfma_f32_32x32x16_bf16 v[48:63], v[76:79], v[204:207], v[48:63]
	ds_read_b64_tr_b16 v[204:205], v223 offset:0x3200
	ds_read_b64_tr_b16 v[206:207], v223 offset:0x3a00
	s_waitcnt lgkmcnt(0)
	v_mfma_f32_32x32x16_bf16 v[32:47], v[64:67], v[192:195], v[32:47]
	ds_read_b64_tr_b16 v[192:193], v223 offset:0x400
	ds_read_b64_tr_b16 v[194:195], v223 offset:0xc00
	v_mfma_f32_32x32x16_bf16 v[32:47], v[68:71], v[196:199], v[32:47]
	ds_read_b64_tr_b16 v[196:197], v223 offset:0x1400
	ds_read_b64_tr_b16 v[198:199], v223 offset:0x1c00
	v_mfma_f32_32x32x16_bf16 v[32:47], v[72:75], v[200:203], v[32:47]
	ds_read_b64_tr_b16 v[200:201], v223 offset:0x2400
	ds_read_b64_tr_b16 v[202:203], v223 offset:0x2c00
	v_mfma_f32_32x32x16_bf16 v[32:47], v[76:79], v[204:207], v[32:47]
	ds_read_b64_tr_b16 v[204:205], v223 offset:0x3400
	ds_read_b64_tr_b16 v[206:207], v223 offset:0x3c00
	s_waitcnt lgkmcnt(0)
	v_mfma_f32_32x32x16_bf16 v[16:31], v[64:67], v[192:195], v[16:31]
	ds_read_b64_tr_b16 v[192:193], v223 offset:0x600
	ds_read_b64_tr_b16 v[194:195], v223 offset:0xe00
	v_mfma_f32_32x32x16_bf16 v[16:31], v[68:71], v[196:199], v[16:31]
	ds_read_b64_tr_b16 v[196:197], v223 offset:0x1600
	ds_read_b64_tr_b16 v[198:199], v223 offset:0x1e00
	v_mfma_f32_32x32x16_bf16 v[16:31], v[72:75], v[200:203], v[16:31]
	ds_read_b64_tr_b16 v[200:201], v223 offset:0x2600
	ds_read_b64_tr_b16 v[202:203], v223 offset:0x2e00
	v_mfma_f32_32x32x16_bf16 v[16:31], v[76:79], v[204:207], v[16:31]
	ds_read_b64_tr_b16 v[204:205], v223 offset:0x3600
	ds_read_b64_tr_b16 v[206:207], v223 offset:0x3e00
	s_waitcnt lgkmcnt(0)
	v_mfma_f32_32x32x16_bf16 v[0:15], v[64:67], v[192:195], v[0:15]
	s_cmp_gt_i32 s34, s18
	s_cselect_b64 s[16:17], -1, 0
	s_cmp_gt_i32 s18, s25
	s_cselect_b64 s[22:23], -1, 0
	s_or_b64 s[16:17], s[16:17], s[22:23]
	s_and_b64 vcc, exec, s[16:17]
	v_mov_b32_e32 v64, 0xf149f2ca
	v_mfma_f32_32x32x16_bf16 v[0:15], v[68:71], v[196:199], v[0:15]
	v_mov_b32_e32 v68, 0xf149f2ca
	v_mov_b32_e32 v69, 0xf149f2ca
	v_mov_b32_e32 v70, 0xf149f2ca
	v_mov_b32_e32 v71, 0xf149f2ca
	v_mov_b32_e32 v65, 0xf149f2ca
	v_mov_b32_e32 v66, 0xf149f2ca
	v_mov_b32_e32 v67, 0xf149f2ca
	v_mfma_f32_32x32x16_bf16 v[0:15], v[72:75], v[200:203], v[0:15]
	v_mov_b32_e32 v72, 0xf149f2ca
	v_mov_b32_e32 v73, 0xf149f2ca
	v_mov_b32_e32 v74, 0xf149f2ca
	v_mov_b32_e32 v75, 0xf149f2ca
	v_mov_b32_e32 v200, 0xf149f2ca
	v_mov_b32_e32 v201, 0xf149f2ca
	v_mov_b32_e32 v202, 0xf149f2ca
	v_mfma_f32_32x32x16_bf16 v[0:15], v[76:79], v[204:207], v[0:15]
	v_mov_b32_e32 v78, 0xf149f2ca
	v_mov_b32_e32 v79, 0xf149f2ca
	v_mov_b32_e32 v76, 0xf149f2ca
	v_mov_b32_e32 v77, 0xf149f2ca
	v_mov_b32_e32 v206, 0xf149f2ca
	v_mov_b32_e32 v207, 0xf149f2ca
	v_mov_b32_e32 v204, 0xf149f2ca
	v_mov_b32_e32 v205, 0xf149f2ca
	v_mov_b32_e32 v203, 0xf149f2ca
	v_mov_b32_e32 v198, 0xf149f2ca
	v_mov_b32_e32 v199, 0xf149f2ca
	v_mov_b32_e32 v196, 0xf149f2ca
	v_mov_b32_e32 v197, 0xf149f2ca
	v_mov_b32_e32 v194, 0xf149f2ca
	v_mov_b32_e32 v195, 0xf149f2ca
	v_mov_b32_e32 v192, 0xf149f2ca
	v_mov_b32_e32 v193, 0xf149f2ca
.Lpvbb_join:
	s_cbranch_vccnz .LBB0_284
	ds_read2_b32 v[64:65], v231 offset0:16 offset1:17
	ds_read2_b32 v[66:67], v231 offset0:18 offset1:19
	ds_read2_b32 v[68:69], v231 offset0:24 offset1:25
	ds_read2_b32 v[70:71], v231 offset0:26 offset1:27
	ds_read2_b32 v[72:73], v231 offset1:1
	ds_read2_b32 v[74:75], v231 offset0:2 offset1:3
	ds_read2_b32 v[76:77], v231 offset0:8 offset1:9
	ds_read2_b32 v[78:79], v231 offset0:10 offset1:11
	s_waitcnt lgkmcnt(4)
	v_pk_fma_f32 v[192:193], v[110:111], s[36:37], v[70:71] op_sel_hi:[1,0,1]
	v_pk_fma_f32 v[194:195], v[108:109], s[36:37], v[68:69] op_sel_hi:[1,0,1]
	v_pk_fma_f32 v[196:197], v[106:107], s[36:37], v[66:67] op_sel_hi:[1,0,1]
	v_pk_fma_f32 v[198:199], v[104:105], s[36:37], v[64:65] op_sel_hi:[1,0,1]
	s_waitcnt lgkmcnt(0)
	v_pk_fma_f32 v[202:203], v[102:103], s[36:37], v[78:79] op_sel_hi:[1,0,1]
	v_pk_fma_f32 v[200:201], v[100:101], s[36:37], v[76:77] op_sel_hi:[1,0,1]
	v_pk_fma_f32 v[204:205], v[98:99], s[36:37], v[74:75] op_sel_hi:[1,0,1]
	v_pk_fma_f32 v[206:207], v[96:97], s[36:37], v[72:73] op_sel_hi:[1,0,1]
	ds_read2_b32 v[68:69], v231 offset0:48 offset1:49
	ds_read2_b32 v[70:71], v231 offset0:50 offset1:51
	ds_read2_b32 v[64:65], v231 offset0:56 offset1:57
	ds_read2_b32 v[66:67], v231 offset0:58 offset1:59
	ds_read2_b32 v[96:97], v231 offset0:32 offset1:33
	ds_read2_b32 v[78:79], v231 offset0:34 offset1:35
	ds_read2_b32 v[76:77], v231 offset0:40 offset1:41
	ds_read2_b32 v[72:73], v231 offset0:42 offset1:43
	s_waitcnt lgkmcnt(4)
	v_pk_fma_f32 v[66:67], v[94:95], s[36:37], v[66:67] op_sel_hi:[1,0,1]
	v_pk_fma_f32 v[64:65], v[92:93], s[36:37], v[64:65] op_sel_hi:[1,0,1]
	v_pk_fma_f32 v[70:71], v[90:91], s[36:37], v[70:71] op_sel_hi:[1,0,1]
	v_pk_fma_f32 v[74:75], v[88:89], s[36:37], v[68:69] op_sel_hi:[1,0,1]
	s_waitcnt lgkmcnt(0)
	v_pk_fma_f32 v[72:73], v[86:87], s[36:37], v[72:73] op_sel_hi:[1,0,1]
	v_pk_fma_f32 v[76:77], v[84:85], s[36:37], v[76:77] op_sel_hi:[1,0,1]
	v_pk_fma_f32 v[78:79], v[82:83], s[36:37], v[78:79] op_sel_hi:[1,0,1]
	v_pk_fma_f32 v[68:69], v[80:81], s[36:37], v[96:97] op_sel_hi:[1,0,1]

; #define LAS __attribute__((address_space(3)))
; template <bool BAND> DI void partialSM(f32x16& p0, f32x16& p1, float& m_reg, float& mn, float& alpha, bool masked, const LAS float* tb, float C) {
;     ...
;   const float mnC = -mn * CC;
; #pragma unroll
;   for (int r = 0; r < 16; ++r) p0[r] = fmaf(p0[r], CC, mnC);
; #pragma unroll
;   for (int r = 0; r < 16; ++r) p1[r] = fmaf(p1[r], CC, mnC);
; #pragma unroll
;   for (int r = 0; r < 16; ++r) p0[r] = __builtin_amdgcn_exp2f(p0[r]);
; }
; DI void finishSM(f32x16& p0, f32x16& p1, float alpha, float& l_reg, bf16x8& pa0, bf16x8& pa1, bf16x8& pa2, bf16x8& pa3) {
; #pragma unroll
;   for (int r = 0; r < 16; ++r) p1[r] = __builtin_amdgcn_exp2f(p1[r]);
;   float ps = 0;
; #pragma unroll
;   for (int r = 0; r < 16; ++r) ps += p0[r];
; #pragma unroll
;   for (int r = 0; r < 16; ++r) ps += p1[r];
;   { auto rr = __builtin_amdgcn_permlane32_swap(__float_as_uint(ps), __float_as_uint(ps), false, false);
;     ps = __uint_as_float(rr[0]) + __uint_as_float(rr[1]); }
;   l_reg = l_reg * alpha + ps;
;     ...
;   PK4(p0, 0, pa0); PK4(p0, 8, pa1); PK4(p1, 0, pa2); PK4(p1, 8, pa3);
;     ...
; }
; template <int NQ> DI void qkt(f32x16& p0, f32x16& p1, const LAS char* Ks, const LAS char* KRs, const bf16x8* qr, int r32, int hi) {
;   p0 = f32x16{}; p1 = f32x16{};
; #pragma unroll
;   for (int d0 = 0; d0 < 8; ++d0) { const int cb = (d0 * 16 + hi * 8) * 2;
;     const bf16x8 b0 = *(const LAS bf16x8*)(Ks + KSWZ(r32, cb));
;     const bf16x8 b1 = *(const LAS bf16x8*)(Ks + KSWZ(32 + r32, cb));
;     p0 = __builtin_amdgcn_mfma_f32_32x32x16_bf16(b0, qr[d0], p0, 0, 0, 0);
;     p1 = __builtin_amdgcn_mfma_f32_32x32x16_bf16(b1, qr[d0], p1, 0, 0, 0); }
.LBB0_288:
	v_cndmask_b32_e64 v228, v80, v228, s[44:45]
	v_sub_f32_e32 v80, v206, v228
	v_sub_f32_e32 v81, v207, v228
	v_sub_f32_e32 v82, v204, v228
	v_sub_f32_e32 v83, v205, v228
	v_sub_f32_e32 v84, v200, v228
	v_sub_f32_e32 v85, v201, v228
	v_sub_f32_e32 v86, v202, v228
	v_sub_f32_e32 v87, v203, v228
	v_sub_f32_e32 v88, v198, v228
	v_sub_f32_e32 v89, v199, v228
	v_sub_f32_e32 v90, v196, v228
	v_sub_f32_e32 v91, v197, v228
	v_sub_f32_e32 v92, v194, v228
	v_sub_f32_e32 v93, v195, v228
	v_sub_f32_e32 v94, v192, v228
	v_sub_f32_e32 v95, v193, v228
	v_exp_f32_e32 v96, v80
	v_exp_f32_e32 v111, v81
	v_exp_f32_e32 v97, v82
	v_exp_f32_e32 v110, v83
	v_exp_f32_e32 v98, v84
	v_exp_f32_e32 v109, v85
	v_exp_f32_e32 v99, v86
	v_exp_f32_e32 v108, v87
	v_exp_f32_e32 v100, v88
	v_exp_f32_e32 v107, v89
	v_exp_f32_e32 v101, v90
	v_exp_f32_e32 v106, v91
	v_exp_f32_e32 v102, v92
	v_exp_f32_e32 v105, v93
	v_exp_f32_e32 v103, v94
	v_exp_f32_e32 v104, v95
	v_sub_f32_e32 v236, v65, v228
	v_sub_f32_e32 v237, v66, v228
	v_sub_f32_e32 v200, v68, v228
	v_sub_f32_e32 v201, v69, v228
	v_sub_f32_e32 v202, v78, v228
	v_sub_f32_e32 v203, v79, v228
	v_sub_f32_e32 v204, v76, v228
	v_sub_f32_e32 v205, v77, v228
	v_sub_f32_e32 v206, v72, v228
	v_sub_f32_e32 v207, v73, v228
	v_sub_f32_e32 v212, v74, v228
	v_sub_f32_e32 v213, v75, v228
	v_sub_f32_e32 v214, v70, v228
	v_sub_f32_e32 v215, v71, v228
	v_sub_f32_e32 v234, v64, v228
	v_sub_f32_e32 v242, v67, v228
	s_waitcnt lgkmcnt(0)
	s_barrier
	s_add_i32 vcc_lo, s18, 1
	s_cmp_gt_i32 s34, vcc_lo
	s_cbranch_scc1 .Lqsba_skip
	s_cmp_ge_i32 s18, s25
	s_cbranch_scc1 .Lqsba_skip
	ds_read_b128 v[64:67], v222 offset:41472
	ds_read_b128 v[68:71], v222 offset:32768
	ds_read_b128 v[192:195], v222 offset:32800
	ds_read_b128 v[196:199], v222 offset:41504
	s_waitcnt lgkmcnt(2)
	v_mfma_f32_32x32x16_bf16 v[80:95], v[68:71], v[144:147], 0
	v_mfma_f32_32x32x16_bf16 v[64:79], v[64:67], v[144:147], 0
	s_waitcnt lgkmcnt(1)
	v_mfma_f32_32x32x16_bf16 v[80:95], v[192:195], v[140:143], v[80:95]
	s_waitcnt lgkmcnt(0)
	v_mfma_f32_32x32x16_bf16 v[64:79], v[196:199], v[140:143], v[64:79]
	ds_read_b128 v[192:195], v222 offset:32832
	ds_read_b128 v[196:199], v222 offset:41536
	s_waitcnt lgkmcnt(1)
	v_mfma_f32_32x32x16_bf16 v[80:95], v[192:195], v[136:139], v[80:95]
	s_waitcnt lgkmcnt(0)
	v_mfma_f32_32x32x16_bf16 v[64:79], v[196:199], v[136:139], v[64:79]
	ds_read_b128 v[192:195], v222 offset:32864
	ds_read_b128 v[196:199], v222 offset:41568
	s_waitcnt lgkmcnt(1)
	v_mfma_f32_32x32x16_bf16 v[80:95], v[192:195], v[132:135], v[80:95]
	s_waitcnt lgkmcnt(0)
	v_mfma_f32_32x32x16_bf16 v[64:79], v[196:199], v[132:135], v[64:79]
	ds_read_b128 v[192:195], v222 offset:32896
	ds_read_b128 v[196:199], v222 offset:41600
	s_waitcnt lgkmcnt(1)
	v_mfma_f32_32x32x16_bf16 v[80:95], v[192:195], v[128:131], v[80:95]
	s_waitcnt lgkmcnt(0)
	v_mfma_f32_32x32x16_bf16 v[64:79], v[196:199], v[128:131], v[64:79]
	ds_read_b128 v[192:195], v222 offset:32928
	ds_read_b128 v[196:199], v222 offset:41632
	s_waitcnt lgkmcnt(1)
	v_mfma_f32_32x32x16_bf16 v[80:95], v[192:195], v[124:127], v[80:95]
	s_waitcnt lgkmcnt(0)
	v_mfma_f32_32x32x16_bf16 v[64:79], v[196:199], v[124:127], v[64:79]
	ds_read_b128 v[192:195], v222 offset:32960
	ds_read_b128 v[196:199], v222 offset:41664
	s_waitcnt lgkmcnt(1)
	v_mfma_f32_32x32x16_bf16 v[80:95], v[192:195], v[120:123], v[80:95]
	s_waitcnt lgkmcnt(0)
	v_mfma_f32_32x32x16_bf16 v[64:79], v[196:199], v[120:123], v[64:79]
	ds_read_b128 v[192:195], v222 offset:32992
	ds_read_b128 v[196:199], v222 offset:41696
	s_waitcnt lgkmcnt(1)
	v_mfma_f32_32x32x16_bf16 v[80:95], v[192:195], v[116:119], v[80:95]
	v_exp_f32_e32 v192, v200
	v_exp_f32_e32 v200, v212
	v_add_f32_e32 v212, 0, v96
	v_add_f32_e32 v212, v111, v212
	v_add_f32_e32 v212, v97, v212
	v_add_f32_e32 v212, v110, v212
	v_add_f32_e32 v212, v98, v212
	v_add_f32_e32 v212, v109, v212
	v_add_f32_e32 v212, v99, v212
	v_add_f32_e32 v212, v108, v212
	v_add_f32_e32 v212, v100, v212
	v_add_f32_e32 v212, v107, v212
	v_add_f32_e32 v212, v101, v212
	v_add_f32_e32 v212, v106, v212
	v_add_f32_e32 v212, v102, v212
	v_exp_f32_e32 v193, v201
	v_add_f32_e32 v212, v105, v212
	v_exp_f32_e32 v194, v202
	v_add_f32_e32 v212, v103, v212
	v_exp_f32_e32 v195, v203
	v_add_f32_e32 v212, v104, v212
	s_waitcnt lgkmcnt(0)
	v_mfma_f32_32x32x16_bf16 v[64:79], v[196:199], v[116:119], v[64:79]
	v_exp_f32_e32 v196, v204
	v_add_f32_e32 v212, v192, v212
	v_exp_f32_e32 v197, v205
	v_add_f32_e32 v212, v193, v212
	v_exp_f32_e32 v198, v206
	v_add_f32_e32 v212, v194, v212
	v_exp_f32_e32 v199, v207
	v_add_f32_e32 v212, v195, v212
	v_add_f32_e32 v212, v196, v212
	v_exp_f32_e32 v201, v213
	v_add_f32_e32 v212, v197, v212
	v_exp_f32_e32 v202, v214
	v_add_f32_e32 v212, v198, v212
	v_exp_f32_e32 v203, v215
	v_add_f32_e32 v212, v199, v212
	v_exp_f32_e32 v204, v234
	v_add_f32_e32 v212, v200, v212
	v_exp_f32_e32 v205, v236
	v_add_f32_e32 v212, v201, v212
	v_exp_f32_e32 v206, v237
	v_add_f32_e32 v212, v202, v212
	v_exp_f32_e32 v207, v242
	v_add_f32_e32 v212, v203, v212
	v_add_f32_e32 v212, v204, v212
	v_add_f32_e32 v212, v205, v212
	v_add_f32_e32 v212, v206, v212
	v_add_f32_e32 v236, v207, v212
	v_mov_b32_e32 v237, v236
	v_cvt_pk_bf16_f32 v96, v96, v111
	v_cvt_pk_bf16_f32 v97, v97, v110
	v_cvt_pk_bf16_f32 v98, v98, v109
	v_cvt_pk_bf16_f32 v99, v99, v108
	v_cvt_pk_bf16_f32 v100, v100, v107
	v_cvt_pk_bf16_f32 v101, v101, v106
	v_cvt_pk_bf16_f32 v102, v102, v105
	v_cvt_pk_bf16_f32 v103, v103, v104
	v_cvt_pk_bf16_f32 v104, v192, v193
	v_cvt_pk_bf16_f32 v105, v194, v195
	v_cvt_pk_bf16_f32 v106, v196, v197
	v_cvt_pk_bf16_f32 v107, v198, v199
	v_cvt_pk_bf16_f32 v108, v200, v201
	v_cvt_pk_bf16_f32 v109, v202, v203
	v_cvt_pk_bf16_f32 v110, v204, v205
	v_cvt_pk_bf16_f32 v111, v206, v207
	s_nop 1
	v_permlane32_swap_b32_e32 v236, v237
	v_permlane32_swap_b32_e32 v96, v98
	v_permlane32_swap_b32_e32 v97, v99
	v_permlane32_swap_b32_e32 v100, v102
	v_permlane32_swap_b32_e32 v101, v103
	v_permlane32_swap_b32_e32 v104, v106
	v_permlane32_swap_b32_e32 v105, v107
	v_permlane32_swap_b32_e32 v108, v110
	v_permlane32_swap_b32_e32 v109, v111
; #define SBAR() __builtin_amdgcn_sched_barrier(0)
; template <int OFF> DI s16x4 tr_read(int vb) { s16x4 r; asm volatile("ds_read_b64_tr_b16 %0, %1 offset:%2" : "=&v"(r) : "v"(vb), "i"(OFF) : "memory"); return r; }
; template <int D0> DI void pv_one(f32x16& od, int vb, bf16x8 pa0, bf16x8 pa1, bf16x8 pa2, bf16x8 pa3) {
;   const s16x4 l0 = tr_read<v_rd_off(D0, 0, 0)>(vb), h0 = tr_read<v_rd_off(D0, 0, 1)>(vb), l1 = tr_read<v_rd_off(D0, 1, 0)>(vb), h1 = tr_read<v_rd_off(D0, 1, 1)>(vb);
;   const s16x4 l2 = tr_read<v_rd_off(D0, 2, 0)>(vb), h2 = tr_read<v_rd_off(D0, 2, 1)>(vb), l3 = tr_read<v_rd_off(D0, 3, 0)>(vb), h3 = tr_read<v_rd_off(D0, 3, 1)>(vb);
;   asm volatile("s_waitcnt lgkmcnt(0)" ::: "memory"); SBAR();
;     ...
;   od = __builtin_amdgcn_mfma_f32_32x32x16_bf16(pa0, PK(l0, h0), od, 0, 0, 0);
;   od = __builtin_amdgcn_mfma_f32_32x32x16_bf16(pa1, PK(l1, h1), od, 0, 0, 0);
;   od = __builtin_amdgcn_mfma_f32_32x32x16_bf16(pa2, PK(l2, h2), od, 0, 0, 0);
;   od = __builtin_amdgcn_mfma_f32_32x32x16_bf16(pa3, PK(l3, h3), od, 0, 0, 0);
;     ...
; }
; DI void pv_d0(f32x16* o, int vb, bf16x8 pa0, bf16x8 pa1, bf16x8 pa2, bf16x8 pa3) {
;   pv_one<0>(o[0], vb, pa0, pa1, pa2, pa3); pv_one<1>(o[1], vb, pa0, pa1, pa2, pa3); pv_one<2>(o[2], vb, pa0, pa1, pa2, pa3); pv_one<3>(o[3], vb, pa0, pa1, pa2, pa3);
.Lqsba_join:
	s_cmp_ge_i32 s49, s21
	s_cselect_b64 s[16:17], -1, 0
	s_and_b64 vcc, exec, s[16:17]
	s_cbranch_vccnz .LBB0_290
	s_min_i32 s22, s49, s35
	s_ashr_i32 s23, s22, 31
	s_lshl_b64 s[22:23], s[22:23], 18
	s_add_u32 s40, s12, s22
	s_addc_u32 s41, s13, s23
	s_add_u32 s22, s14, s22
	s_addc_u32 s23, s15, s23
	v_lshl_add_u64 v[148:149], s[22:23], 0, v[112:113]
	v_lshl_add_u64 v[152:153], s[22:23], 0, v[114:115]
	v_lshl_add_u64 v[156:157], s[40:41], 0, v[112:113]
	v_lshl_add_u64 v[160:161], s[40:41], 0, v[114:115]
	global_load_dwordx4 v[148:151], v[148:149], off
	s_nop 0
	global_load_dwordx4 v[152:155], v[152:153], off
	s_nop 0
	global_load_dwordx4 v[156:159], v[156:157], off
	s_nop 0
	global_load_dwordx4 v[160:163], v[160:161], off
	s_mov_b32 s40, 0x41380000
.LBB0_290:
	s_add_i32 s19, s49, -2
	s_cmp_gt_i32 s34, s18
	s_cbranch_scc1 .Lpvba_skip
	s_cmp_gt_i32 s18, s25
	s_cbranch_scc1 .Lpvba_skip
	ds_read_b64_tr_b16 v[192:193], v230 offset:0
	ds_read_b64_tr_b16 v[194:195], v230 offset:0x800
	ds_read_b64_tr_b16 v[196:197], v230 offset:0x1000
	ds_read_b64_tr_b16 v[198:199], v230 offset:0x1800
	ds_read_b64_tr_b16 v[200:201], v230 offset:0x2000
	ds_read_b64_tr_b16 v[202:203], v230 offset:0x2800
	ds_read_b64_tr_b16 v[204:205], v230 offset:0x3000
	ds_read_b64_tr_b16 v[206:207], v230 offset:0x3800
	s_waitcnt lgkmcnt(0)
	s_nop 0
	v_mfma_f32_32x32x16_bf16 v[48:63], v[96:99], v[192:195], v[48:63]
	ds_read_b64_tr_b16 v[192:193], v230 offset:0x200
	ds_read_b64_tr_b16 v[194:195], v230 offset:0xa00
	v_mfma_f32_32x32x16_bf16 v[48:63], v[100:103], v[196:199], v[48:63]
	ds_read_b64_tr_b16 v[196:197], v230 offset:0x1200
	ds_read_b64_tr_b16 v[198:199], v230 offset:0x1a00
	v_mfma_f32_32x32x16_bf16 v[48:63], v[104:107], v[200:203], v[48:63]
	ds_read_b64_tr_b16 v[200:201], v230 offset:0x2200
	ds_read_b64_tr_b16 v[202:203], v230 offset:0x2a00
	v_mfma_f32_32x32x16_bf16 v[48:63], v[108:111], v[204:207], v[48:63]
	ds_read_b64_tr_b16 v[204:205], v230 offset:0x3200
	ds_read_b64_tr_b16 v[206:207], v230 offset:0x3a00
	s_waitcnt lgkmcnt(0)
	v_mfma_f32_32x32x16_bf16 v[32:47], v[96:99], v[192:195], v[32:47]
	ds_read_b64_tr_b16 v[192:193], v230 offset:0x400
	ds_read_b64_tr_b16 v[194:195], v230 offset:0xc00
	v_mfma_f32_32x32x16_bf16 v[32:47], v[100:103], v[196:199], v[32:47]
	ds_read_b64_tr_b16 v[196:197], v230 offset:0x1400
	ds_read_b64_tr_b16 v[198:199], v230 offset:0x1c00
	v_mfma_f32_32x32x16_bf16 v[32:47], v[104:107], v[200:203], v[32:47]
	ds_read_b64_tr_b16 v[200:201], v230 offset:0x2400
	ds_read_b64_tr_b16 v[202:203], v230 offset:0x2c00
	v_mfma_f32_32x32x16_bf16 v[32:47], v[108:111], v[204:207], v[32:47]
	ds_read_b64_tr_b16 v[204:205], v230 offset:0x3400
	ds_read_b64_tr_b16 v[206:207], v230 offset:0x3c00
	s_waitcnt lgkmcnt(0)
	v_mfma_f32_32x32x16_bf16 v[16:31], v[96:99], v[192:195], v[16:31]
	ds_read_b64_tr_b16 v[192:193], v230 offset:0x600
	ds_read_b64_tr_b16 v[194:195], v230 offset:0xe00
	v_mfma_f32_32x32x16_bf16 v[16:31], v[100:103], v[196:199], v[16:31]
	ds_read_b64_tr_b16 v[196:197], v230 offset:0x1600
	ds_read_b64_tr_b16 v[198:199], v230 offset:0x1e00
	v_mfma_f32_32x32x16_bf16 v[16:31], v[104:107], v[200:203], v[16:31]
	ds_read_b64_tr_b16 v[200:201], v230 offset:0x2600
	ds_read_b64_tr_b16 v[202:203], v230 offset:0x2e00
	v_mfma_f32_32x32x16_bf16 v[16:31], v[108:111], v[204:207], v[16:31]
	ds_read_b64_tr_b16 v[204:205], v230 offset:0x3600
	ds_read_b64_tr_b16 v[206:207], v230 offset:0x3e00
	s_waitcnt lgkmcnt(0)
	v_mfma_f32_32x32x16_bf16 v[0:15], v[96:99], v[192:195], v[0:15]
	s_cmp_gt_i32 s34, s19
	s_cselect_b64 s[22:23], -1, 0
	s_cmp_ge_i32 s18, s25
	s_cselect_b64 s[18:19], -1, 0
	s_or_b64 s[18:19], s[22:23], s[18:19]
	v_mov_b32_e32 v96, 0xf149f2ca
	s_and_b64 vcc, exec, s[18:19]
	v_mfma_f32_32x32x16_bf16 v[0:15], v[100:103], v[196:199], v[0:15]
	v_mov_b32_e32 v97, 0xf149f2ca
	v_mov_b32_e32 v98, 0xf149f2ca
	v_mov_b32_e32 v99, 0xf149f2ca
	v_mov_b32_e32 v100, 0xf149f2ca
	v_mov_b32_e32 v101, 0xf149f2ca
	v_mov_b32_e32 v102, 0xf149f2ca
	v_mov_b32_e32 v103, 0xf149f2ca
	v_mfma_f32_32x32x16_bf16 v[0:15], v[104:107], v[200:203], v[0:15]
	v_mov_b32_e32 v104, 0xf149f2ca
	v_mov_b32_e32 v105, 0xf149f2ca
	v_mov_b32_e32 v106, 0xf149f2ca
	v_mov_b32_e32 v107, 0xf149f2ca
	v_mov_b32_e32 v200, 0xf149f2ca
	v_mov_b32_e32 v201, 0xf149f2ca
	v_mov_b32_e32 v202, 0xf149f2ca
	v_mfma_f32_32x32x16_bf16 v[0:15], v[108:111], v[204:207], v[0:15]
	v_mov_b32_e32 v108, 0xf149f2ca
	v_mov_b32_e32 v109, 0xf149f2ca
	v_mov_b32_e32 v110, 0xf149f2ca
	v_mov_b32_e32 v111, 0xf149f2ca
	v_mov_b32_e32 v206, 0xf149f2ca
	v_mov_b32_e32 v207, 0xf149f2ca
	v_mov_b32_e32 v204, 0xf149f2ca
	v_mov_b32_e32 v205, 0xf149f2ca
	v_mov_b32_e32 v203, 0xf149f2ca
	v_mov_b32_e32 v198, 0xf149f2ca
	v_mov_b32_e32 v199, 0xf149f2ca
	v_mov_b32_e32 v196, 0xf149f2ca
	v_mov_b32_e32 v197, 0xf149f2ca
	v_mov_b32_e32 v194, 0xf149f2ca
	v_mov_b32_e32 v195, 0xf149f2ca
	v_mov_b32_e32 v192, 0xf149f2ca
	v_mov_b32_e32 v193, 0xf149f2ca
; #define SBAR() __builtin_amdgcn_sched_barrier(0)
; template <bool BAND> DI void partialSM(f32x16& p0, f32x16& p1, float& m_reg, float& mn, float& alpha, bool masked, const LAS float* tb, float C) {
;     ...
;   } else if (BAND) {
; #pragma unroll
;     for (int r = 0; r < 16; ++r) { const int ko = (r & 3) + 8 * (r >> 2); p0[r] = fmaf(p0[r], C, tb[ko]); }
;     SBAR();
; #pragma unroll
;     for (int r = 0; r < 16; ++r) { const int ko = (r & 3) + 8 * (r >> 2); p1[r] = fmaf(p1[r], C, tb[ko + 32]); }
.Lpvba_join:
	s_cbranch_vccnz .LBB0_292
	ds_read2_b32 v[96:97], v231 offset0:80 offset1:81
	ds_read2_b32 v[98:99], v231 offset0:82 offset1:83
	ds_read2_b32 v[100:101], v231 offset0:88 offset1:89
	ds_read2_b32 v[102:103], v231 offset0:90 offset1:91
	ds_read2_b32 v[104:105], v231 offset0:64 offset1:65
	ds_read2_b32 v[106:107], v231 offset0:66 offset1:67
	ds_read2_b32 v[108:109], v231 offset0:72 offset1:73
	ds_read2_b32 v[110:111], v231 offset0:74 offset1:75
	s_waitcnt lgkmcnt(4)
	v_pk_fma_f32 v[192:193], v[94:95], s[36:37], v[102:103] op_sel_hi:[1,0,1]
	v_pk_fma_f32 v[194:195], v[92:93], s[36:37], v[100:101] op_sel_hi:[1,0,1]
	v_pk_fma_f32 v[196:197], v[90:91], s[36:37], v[98:99] op_sel_hi:[1,0,1]
	v_pk_fma_f32 v[198:199], v[88:89], s[36:37], v[96:97] op_sel_hi:[1,0,1]
	s_waitcnt lgkmcnt(0)
	v_pk_fma_f32 v[202:203], v[86:87], s[36:37], v[110:111] op_sel_hi:[1,0,1]
	v_pk_fma_f32 v[200:201], v[84:85], s[36:37], v[108:109] op_sel_hi:[1,0,1]
	v_pk_fma_f32 v[204:205], v[82:83], s[36:37], v[106:107] op_sel_hi:[1,0,1]
	v_pk_fma_f32 v[206:207], v[80:81], s[36:37], v[104:105] op_sel_hi:[1,0,1]
	ds_read2_b32 v[80:81], v231 offset0:112 offset1:113
	ds_read2_b32 v[82:83], v231 offset0:114 offset1:115
	ds_read2_b32 v[84:85], v231 offset0:120 offset1:121
	ds_read2_b32 v[86:87], v231 offset0:122 offset1:123
	ds_read2_b32 v[88:89], v231 offset0:96 offset1:97
	ds_read2_b32 v[90:91], v231 offset0:98 offset1:99
	ds_read2_b32 v[92:93], v231 offset0:104 offset1:105
	ds_read2_b32 v[94:95], v231 offset0:106 offset1:107
	s_waitcnt lgkmcnt(4)
	v_pk_fma_f32 v[110:111], v[78:79], s[36:37], v[86:87] op_sel_hi:[1,0,1]
	v_pk_fma_f32 v[108:109], v[76:77], s[36:37], v[84:85] op_sel_hi:[1,0,1]
	v_pk_fma_f32 v[106:107], v[74:75], s[36:37], v[82:83] op_sel_hi:[1,0,1]
	v_pk_fma_f32 v[104:105], v[72:73], s[36:37], v[80:81] op_sel_hi:[1,0,1]
	s_waitcnt lgkmcnt(0)
	v_pk_fma_f32 v[102:103], v[70:71], s[36:37], v[94:95] op_sel_hi:[1,0,1]
	v_pk_fma_f32 v[100:101], v[68:69], s[36:37], v[92:93] op_sel_hi:[1,0,1]
	v_pk_fma_f32 v[98:99], v[66:67], s[36:37], v[90:91] op_sel_hi:[1,0,1]
	v_pk_fma_f32 v[96:97], v[64:65], s[36:37], v[88:89] op_sel_hi:[1,0,1]

; DI void finishSM(f32x16& p0, f32x16& p1, float alpha, float& l_reg, bf16x8& pa0, bf16x8& pa1, bf16x8& pa2, bf16x8& pa3) {
; #pragma unroll
;   for (int r = 0; r < 16; ++r) p1[r] = __builtin_amdgcn_exp2f(p1[r]);
;   float ps = 0;
; #pragma unroll
;   for (int r = 0; r < 16; ++r) ps += p0[r];
; #pragma unroll
;   for (int r = 0; r < 16; ++r) ps += p1[r];
;   { auto rr = __builtin_amdgcn_permlane32_swap(__float_as_uint(ps), __float_as_uint(ps), false, false);
;     ps = __uint_as_float(rr[0]) + __uint_as_float(rr[1]); }
;   l_reg = l_reg * alpha + ps;
;     ...
;   PK4(p0, 0, pa0); PK4(p0, 8, pa1); PK4(p1, 0, pa2); PK4(p1, 8, pa3);
.Lqsbb_skip:
	v_exp_f32_e32 v200, v64
	v_add_f32_e32 v64, 0, v177
	v_add_f32_e32 v64, v179, v64
	v_add_f32_e32 v64, v175, v64
	v_add_f32_e32 v64, v178, v64
	v_add_f32_e32 v64, v174, v64
	v_add_f32_e32 v64, v176, v64
	v_add_f32_e32 v64, v172, v64
	v_add_f32_e32 v64, v173, v64
	v_add_f32_e32 v64, v169, v64
	v_add_f32_e32 v64, v171, v64
	v_add_f32_e32 v64, v168, v64
	v_add_f32_e32 v64, v170, v64
	v_exp_f32_e32 v78, v78
	v_add_f32_e32 v64, v165, v64
	v_exp_f32_e32 v79, v79
	v_add_f32_e32 v64, v167, v64
	v_exp_f32_e32 v76, v76
	v_add_f32_e32 v64, v164, v64
	v_exp_f32_e32 v77, v77
	v_add_f32_e32 v64, v166, v64
	v_exp_f32_e32 v74, v74
	v_add_f32_e32 v64, v78, v64
	v_exp_f32_e32 v75, v75
	v_add_f32_e32 v64, v79, v64
	v_add_f32_e32 v64, v76, v64
	v_add_f32_e32 v64, v77, v64
	v_add_f32_e32 v64, v74, v64
	v_add_f32_e32 v64, v75, v64
	v_exp_f32_e32 v201, v65
	v_exp_f32_e32 v192, v72
	v_exp_f32_e32 v193, v73
	v_exp_f32_e32 v194, v70
	v_exp_f32_e32 v195, v71
	v_add_f32_e32 v64, v192, v64
	v_add_f32_e32 v64, v193, v64
	v_add_f32_e32 v64, v194, v64
	v_exp_f32_e32 v196, v68
	v_exp_f32_e32 v197, v69
	v_exp_f32_e32 v198, v66
	v_exp_f32_e32 v199, v67
	v_add_f32_e32 v64, v195, v64
	v_add_f32_e32 v64, v196, v64
	v_add_f32_e32 v64, v197, v64
	v_add_f32_e32 v64, v198, v64
	v_add_f32_e32 v64, v199, v64
	v_add_f32_e32 v64, v200, v64
	v_add_f32_e32 v232, v201, v64
	v_mov_b32_e32 v233, v232
	v_cvt_pk_bf16_f32 v64, v177, v179
	v_cvt_pk_bf16_f32 v65, v175, v178
	v_cvt_pk_bf16_f32 v66, v174, v176
	v_cvt_pk_bf16_f32 v67, v172, v173
	v_cvt_pk_bf16_f32 v68, v169, v171
	v_cvt_pk_bf16_f32 v69, v168, v170
	v_cvt_pk_bf16_f32 v70, v165, v167
	v_cvt_pk_bf16_f32 v71, v164, v166
	v_cvt_pk_bf16_f32 v72, v78, v79
	v_cvt_pk_bf16_f32 v73, v76, v77
	v_cvt_pk_bf16_f32 v74, v74, v75
	v_cvt_pk_bf16_f32 v75, v192, v193
	v_cvt_pk_bf16_f32 v76, v194, v195
	v_cvt_pk_bf16_f32 v77, v196, v197
	v_cvt_pk_bf16_f32 v78, v198, v199
	v_cvt_pk_bf16_f32 v79, v200, v201
	s_nop 1
	v_permlane32_swap_b32_e32 v232, v233
	v_permlane32_swap_b32_e32 v64, v66
	v_permlane32_swap_b32_e32 v65, v67
	v_permlane32_swap_b32_e32 v68, v70
	v_permlane32_swap_b32_e32 v69, v71
	v_permlane32_swap_b32_e32 v72, v74
	v_permlane32_swap_b32_e32 v73, v75
	v_permlane32_swap_b32_e32 v76, v78
	v_permlane32_swap_b32_e32 v77, v79
	s_branch .Lqsbb_join
.Lqsba_skip:
	v_exp_f32_e32 v192, v200
	v_exp_f32_e32 v200, v212
	v_add_f32_e32 v212, 0, v96
	v_add_f32_e32 v212, v111, v212
	v_add_f32_e32 v212, v97, v212
	v_add_f32_e32 v212, v110, v212
	v_add_f32_e32 v212, v98, v212
	v_add_f32_e32 v212, v109, v212
	v_add_f32_e32 v212, v99, v212
	v_add_f32_e32 v212, v108, v212
	v_add_f32_e32 v212, v100, v212
	v_add_f32_e32 v212, v107, v212
	v_add_f32_e32 v212, v101, v212
	v_add_f32_e32 v212, v106, v212
	v_add_f32_e32 v212, v102, v212
	v_exp_f32_e32 v193, v201
	v_add_f32_e32 v212, v105, v212
	v_exp_f32_e32 v194, v202
	v_add_f32_e32 v212, v103, v212
	v_exp_f32_e32 v195, v203
	v_add_f32_e32 v212, v104, v212
	v_exp_f32_e32 v196, v204
	v_add_f32_e32 v212, v192, v212
	v_exp_f32_e32 v197, v205
	v_add_f32_e32 v212, v193, v212
	v_exp_f32_e32 v198, v206
	v_add_f32_e32 v212, v194, v212
	v_exp_f32_e32 v199, v207
	v_add_f32_e32 v212, v195, v212
	v_add_f32_e32 v212, v196, v212
	v_exp_f32_e32 v201, v213
	v_add_f32_e32 v212, v197, v212
	v_exp_f32_e32 v202, v214
	v_add_f32_e32 v212, v198, v212
	v_exp_f32_e32 v203, v215
	v_add_f32_e32 v212, v199, v212
	v_exp_f32_e32 v204, v234
	v_add_f32_e32 v212, v200, v212
	v_exp_f32_e32 v205, v236
	v_add_f32_e32 v212, v201, v212
	v_exp_f32_e32 v206, v237
	v_add_f32_e32 v212, v202, v212
	v_exp_f32_e32 v207, v242
	v_add_f32_e32 v212, v203, v212
	v_add_f32_e32 v212, v204, v212
	v_add_f32_e32 v212, v205, v212
	v_add_f32_e32 v212, v206, v212
	v_add_f32_e32 v236, v207, v212
	v_mov_b32_e32 v237, v236
	v_cvt_pk_bf16_f32 v96, v96, v111
	v_cvt_pk_bf16_f32 v97, v97, v110
	v_cvt_pk_bf16_f32 v98, v98, v109
	v_cvt_pk_bf16_f32 v99, v99, v108
	v_cvt_pk_bf16_f32 v100, v100, v107
	v_cvt_pk_bf16_f32 v101, v101, v106
	v_cvt_pk_bf16_f32 v102, v102, v105
	v_cvt_pk_bf16_f32 v103, v103, v104
	v_cvt_pk_bf16_f32 v104, v192, v193
	v_cvt_pk_bf16_f32 v105, v194, v195
	v_cvt_pk_bf16_f32 v106, v196, v197
	v_cvt_pk_bf16_f32 v107, v198, v199
	v_cvt_pk_bf16_f32 v108, v200, v201
	v_cvt_pk_bf16_f32 v109, v202, v203
	v_cvt_pk_bf16_f32 v110, v204, v205
	v_cvt_pk_bf16_f32 v111, v206, v207
	s_nop 1
	v_permlane32_swap_b32_e32 v236, v237
	v_permlane32_swap_b32_e32 v96, v98
	v_permlane32_swap_b32_e32 v97, v99
	v_permlane32_swap_b32_e32 v100, v102
	v_permlane32_swap_b32_e32 v101, v103
	v_permlane32_swap_b32_e32 v104, v106
	v_permlane32_swap_b32_e32 v105, v107
	v_permlane32_swap_b32_e32 v108, v110
	v_permlane32_swap_b32_e32 v109, v111
	s_branch .Lqsba_join
; #define LAS __attribute__((address_space(3)))
; template <bool BAND> DI void partialSM(f32x16& p0, f32x16& p1, float& m_reg, float& mn, float& alpha, bool masked, const LAS float* tb, float C) {
;   if (masked) {
; #pragma unroll
;     for (int r = 0; r < 16; ++r) { p0[r] = -1e30f; p1[r] = -1e30f; }
.Lpvbb_skip:
	s_nop 0
	s_cmp_gt_i32 s34, s18
	s_cselect_b64 s[16:17], -1, 0
	s_cmp_gt_i32 s18, s25
	s_cselect_b64 s[22:23], -1, 0
	s_or_b64 s[16:17], s[16:17], s[22:23]
	s_and_b64 vcc, exec, s[16:17]
	v_mov_b32_e32 v64, 0xf149f2ca
	v_mov_b32_e32 v68, 0xf149f2ca
	v_mov_b32_e32 v69, 0xf149f2ca
	v_mov_b32_e32 v70, 0xf149f2ca
	v_mov_b32_e32 v71, 0xf149f2ca
	v_mov_b32_e32 v65, 0xf149f2ca
	v_mov_b32_e32 v66, 0xf149f2ca
	v_mov_b32_e32 v67, 0xf149f2ca
	v_mov_b32_e32 v72, 0xf149f2ca
	v_mov_b32_e32 v73, 0xf149f2ca
	v_mov_b32_e32 v74, 0xf149f2ca
	v_mov_b32_e32 v75, 0xf149f2ca
	v_mov_b32_e32 v200, 0xf149f2ca
	v_mov_b32_e32 v201, 0xf149f2ca
	v_mov_b32_e32 v202, 0xf149f2ca
	v_mov_b32_e32 v78, 0xf149f2ca
	v_mov_b32_e32 v79, 0xf149f2ca
	v_mov_b32_e32 v76, 0xf149f2ca
	v_mov_b32_e32 v77, 0xf149f2ca
	v_mov_b32_e32 v206, 0xf149f2ca
	v_mov_b32_e32 v207, 0xf149f2ca
	v_mov_b32_e32 v204, 0xf149f2ca
	v_mov_b32_e32 v205, 0xf149f2ca
	v_mov_b32_e32 v203, 0xf149f2ca
	v_mov_b32_e32 v198, 0xf149f2ca
	v_mov_b32_e32 v199, 0xf149f2ca
	v_mov_b32_e32 v196, 0xf149f2ca
	v_mov_b32_e32 v197, 0xf149f2ca
	v_mov_b32_e32 v194, 0xf149f2ca
	v_mov_b32_e32 v195, 0xf149f2ca
	v_mov_b32_e32 v192, 0xf149f2ca
	v_mov_b32_e32 v193, 0xf149f2ca
	s_branch .Lpvbb_join
.Lpvba_skip:
	s_nop 0
	s_cmp_gt_i32 s34, s19
	s_cselect_b64 s[22:23], -1, 0
	s_cmp_ge_i32 s18, s25
	s_cselect_b64 s[18:19], -1, 0
	s_or_b64 s[18:19], s[22:23], s[18:19]
	v_mov_b32_e32 v96, 0xf149f2ca
	s_and_b64 vcc, exec, s[18:19]
	v_mov_b32_e32 v97, 0xf149f2ca
	v_mov_b32_e32 v98, 0xf149f2ca
	v_mov_b32_e32 v99, 0xf149f2ca
	v_mov_b32_e32 v100, 0xf149f2ca
	v_mov_b32_e32 v101, 0xf149f2ca
	v_mov_b32_e32 v102, 0xf149f2ca
	v_mov_b32_e32 v103, 0xf149f2ca
	v_mov_b32_e32 v104, 0xf149f2ca
	v_mov_b32_e32 v105, 0xf149f2ca
	v_mov_b32_e32 v106, 0xf149f2ca
	v_mov_b32_e32 v107, 0xf149f2ca
	v_mov_b32_e32 v200, 0xf149f2ca
	v_mov_b32_e32 v201, 0xf149f2ca
	v_mov_b32_e32 v202, 0xf149f2ca
	v_mov_b32_e32 v108, 0xf149f2ca
	v_mov_b32_e32 v109, 0xf149f2ca
	v_mov_b32_e32 v110, 0xf149f2ca
	v_mov_b32_e32 v111, 0xf149f2ca
	v_mov_b32_e32 v206, 0xf149f2ca
	v_mov_b32_e32 v207, 0xf149f2ca
	v_mov_b32_e32 v204, 0xf149f2ca
	v_mov_b32_e32 v205, 0xf149f2ca
	v_mov_b32_e32 v203, 0xf149f2ca
	v_mov_b32_e32 v198, 0xf149f2ca
	v_mov_b32_e32 v199, 0xf149f2ca
	v_mov_b32_e32 v196, 0xf149f2ca
	v_mov_b32_e32 v197, 0xf149f2ca
	v_mov_b32_e32 v194, 0xf149f2ca
	v_mov_b32_e32 v195, 0xf149f2ca
	v_mov_b32_e32 v192, 0xf149f2ca
	v_mov_b32_e32 v193, 0xf149f2ca
	s_branch .Lpvba_join

; #define LAS __attribute__((address_space(3)))
; DI void finishSM(f32x16& p0, f32x16& p1, float alpha, float& l_reg, bf16x8& pa0, bf16x8& pa1, bf16x8& pa2, bf16x8& pa3) {
; #pragma unroll
;   for (int r = 0; r < 16; ++r) p1[r] = __builtin_amdgcn_exp2f(p1[r]);
;   float ps = 0;
; #pragma unroll
;   for (int r = 0; r < 16; ++r) ps += p0[r];
; #pragma unroll
;   for (int r = 0; r < 16; ++r) ps += p1[r];
;   { auto rr = __builtin_amdgcn_permlane32_swap(__float_as_uint(ps), __float_as_uint(ps), false, false);
;     ps = __uint_as_float(rr[0]) + __uint_as_float(rr[1]); }
;   l_reg = l_reg * alpha + ps;
;     ...
;   PK4(p0, 0, pa0); PK4(p0, 8, pa1); PK4(p1, 0, pa2); PK4(p1, 8, pa3);
;     ...
; }
; template <int NQ> DI void qkt(f32x16& p0, f32x16& p1, const LAS char* Ks, const LAS char* KRs, const bf16x8* qr, int r32, int hi) {
;   p0 = f32x16{}; p1 = f32x16{};
; #pragma unroll
;   for (int d0 = 0; d0 < 8; ++d0) { const int cb = (d0 * 16 + hi * 8) * 2;
;     const bf16x8 b0 = *(const LAS bf16x8*)(Ks + KSWZ(r32, cb));
;     const bf16x8 b1 = *(const LAS bf16x8*)(Ks + KSWZ(32 + r32, cb));
;     p0 = __builtin_amdgcn_mfma_f32_32x32x16_bf16(b0, qr[d0], p0, 0, 0, 0);
;     p1 = __builtin_amdgcn_mfma_f32_32x32x16_bf16(b1, qr[d0], p1, 0, 0, 0); }
;   if (NQ == 12) {
; #pragma unroll
;     for (int d0 = 0; d0 < 4; ++d0) { const int cb = (d0 * 16 + hi * 8) * 2;
;       const bf16x8 b0 = *(const LAS bf16x8*)(KRs + KRSWZ(r32, cb));
;       const bf16x8 b1 = *(const LAS bf16x8*)(KRs + KRSWZ(32 + r32, cb));
;       p0 = __builtin_amdgcn_mfma_f32_32x32x16_bf16(b0, qr[8 + d0], p0, 0, 0, 0);
;       p1 = __builtin_amdgcn_mfma_f32_32x32x16_bf16(b1, qr[8 + d0], p1, 0, 0, 0); }
;   }
.LBB0_344:
	s_add_i32 s39, s35, -1
	s_add_i32 s37, s35, -2
	s_cmp_gt_i32 s34, s37
	s_cbranch_scc1 .Lqsmb_skip
	s_cmp_gt_i32 s37, s21
	s_cbranch_scc1 .Lqsmb_skip
	ds_read_b128 v[90:93], v207 offset:58880
	ds_read_b128 v[74:77], v207 offset:50176
	ds_read_b128 v[220:223], v207 offset:50208
	ds_read_b128 v[224:227], v207 offset:58912
	v_exp_f32_e32 v170, v170
	s_waitcnt lgkmcnt(3)
	v_mfma_f32_32x32x16_bf16 v[90:105], v[90:93], v[160:163], 0
	v_exp_f32_e32 v171, v171
	v_exp_f32_e32 v168, v168
	v_exp_f32_e32 v169, v169
	s_waitcnt lgkmcnt(2)
	v_mfma_f32_32x32x16_bf16 v[74:89], v[74:77], v[160:163], 0
	s_waitcnt lgkmcnt(1)
	v_mfma_f32_32x32x16_bf16 v[74:89], v[220:223], v[156:159], v[74:89]
	s_waitcnt lgkmcnt(0)
	v_mfma_f32_32x32x16_bf16 v[90:105], v[224:227], v[156:159], v[90:105]
	ds_read_b128 v[220:223], v207 offset:50240
	ds_read_b128 v[224:227], v207 offset:58944
	s_waitcnt lgkmcnt(1)
	v_mfma_f32_32x32x16_bf16 v[74:89], v[220:223], v[152:155], v[74:89]
	s_waitcnt lgkmcnt(0)
	v_mfma_f32_32x32x16_bf16 v[90:105], v[224:227], v[152:155], v[90:105]
	ds_read_b128 v[220:223], v207 offset:50272
	ds_read_b128 v[224:227], v207 offset:58976
	s_waitcnt lgkmcnt(1)
	v_mfma_f32_32x32x16_bf16 v[74:89], v[220:223], v[148:151], v[74:89]
	s_waitcnt lgkmcnt(0)
	v_mfma_f32_32x32x16_bf16 v[90:105], v[224:227], v[148:151], v[90:105]
	ds_read_b128 v[220:223], v207 offset:50304
	ds_read_b128 v[224:227], v207 offset:59008
	s_waitcnt lgkmcnt(1)
	v_mfma_f32_32x32x16_bf16 v[74:89], v[220:223], v[144:147], v[74:89]
	s_waitcnt lgkmcnt(0)
	v_mfma_f32_32x32x16_bf16 v[90:105], v[224:227], v[144:147], v[90:105]
	ds_read_b128 v[220:223], v207 offset:50336
	ds_read_b128 v[224:227], v207 offset:59040
	s_waitcnt lgkmcnt(1)
	v_mfma_f32_32x32x16_bf16 v[74:89], v[220:223], v[140:143], v[74:89]
	s_waitcnt lgkmcnt(0)
	v_mfma_f32_32x32x16_bf16 v[90:105], v[224:227], v[140:143], v[90:105]
	ds_read_b128 v[220:223], v207 offset:50368
	ds_read_b128 v[224:227], v207 offset:59072
	s_waitcnt lgkmcnt(1)
	v_mfma_f32_32x32x16_bf16 v[74:89], v[220:223], v[136:139], v[74:89]
	s_waitcnt lgkmcnt(0)
	v_mfma_f32_32x32x16_bf16 v[90:105], v[224:227], v[136:139], v[90:105]
	ds_read_b128 v[220:223], v207 offset:50400
	ds_read_b128 v[224:227], v207 offset:59104
	s_waitcnt lgkmcnt(1)
	v_mfma_f32_32x32x16_bf16 v[74:89], v[220:223], v[132:135], v[74:89]
	s_waitcnt lgkmcnt(0)
	v_mfma_f32_32x32x16_bf16 v[90:105], v[224:227], v[132:135], v[90:105]
	ds_read_b128 v[220:223], v218 offset:4608
	ds_read_b128 v[224:227], v218
	ds_read_b128 v[228:231], v218 offset:32
	s_waitcnt lgkmcnt(1)
	v_mfma_f32_32x32x16_bf16 v[74:89], v[224:227], v[128:131], v[74:89]
	v_mfma_f32_32x32x16_bf16 v[90:105], v[220:223], v[128:131], v[90:105]
	ds_read_b128 v[220:223], v218 offset:4640
	s_waitcnt lgkmcnt(1)
	v_mfma_f32_32x32x16_bf16 v[74:89], v[228:231], v[124:127], v[74:89]
	s_waitcnt lgkmcnt(0)
	v_mfma_f32_32x32x16_bf16 v[90:105], v[220:223], v[124:127], v[90:105]
	ds_read_b128 v[220:223], v218 offset:64
	ds_read_b128 v[224:227], v218 offset:4672
	s_waitcnt lgkmcnt(1)
	v_mfma_f32_32x32x16_bf16 v[74:89], v[220:223], v[120:123], v[74:89]
	s_waitcnt lgkmcnt(0)
	v_mfma_f32_32x32x16_bf16 v[90:105], v[224:227], v[120:123], v[90:105]
	ds_read_b128 v[220:223], v218 offset:96
	ds_read_b128 v[224:227], v218 offset:4704
	s_waitcnt lgkmcnt(1)
	v_mfma_f32_32x32x16_bf16 v[74:89], v[220:223], v[116:119], v[74:89]
	v_exp_f32_e32 v222, v174
	v_exp_f32_e32 v174, v164
	v_add_f32_e32 v164, 0, v110
	v_add_f32_e32 v164, v111, v164
	v_add_f32_e32 v164, v108, v164
	v_add_f32_e32 v164, v109, v164
	v_add_f32_e32 v164, v106, v164
	v_add_f32_e32 v164, v107, v164
	v_add_f32_e32 v164, v72, v164
	v_add_f32_e32 v164, v73, v164
	v_add_f32_e32 v164, v66, v164
	v_add_f32_e32 v164, v67, v164
	v_add_f32_e32 v164, v64, v164
	v_add_f32_e32 v164, v65, v164
	s_waitcnt lgkmcnt(0)
	v_mfma_f32_32x32x16_bf16 v[90:105], v[224:227], v[116:119], v[90:105]
	v_exp_f32_e32 v225, v196
	v_add_f32_e32 v164, v68, v164
	v_exp_f32_e32 v227, v197
	v_add_f32_e32 v164, v69, v164
	v_exp_f32_e32 v196, v178
	v_add_f32_e32 v164, v70, v164
	v_exp_f32_e32 v197, v179
	v_add_f32_e32 v164, v71, v164
	v_add_f32_e32 v164, v225, v164
	v_exp_f32_e32 v223, v175
	v_add_f32_e32 v164, v227, v164
	v_exp_f32_e32 v224, v172
	v_add_f32_e32 v164, v196, v164
	v_exp_f32_e32 v226, v173
	v_add_f32_e32 v164, v197, v164
	v_add_f32_e32 v164, v222, v164
	v_add_f32_e32 v164, v223, v164
	v_add_f32_e32 v164, v224, v164
	v_add_f32_e32 v164, v226, v164
	v_exp_f32_e32 v172, v166
	v_add_f32_e32 v164, v170, v164
	v_exp_f32_e32 v173, v167
	v_add_f32_e32 v164, v171, v164
	v_add_f32_e32 v164, v168, v164
	v_exp_f32_e32 v175, v165
	v_add_f32_e32 v164, v169, v164
	v_add_f32_e32 v164, v172, v164
	v_add_f32_e32 v164, v173, v164
	v_add_f32_e32 v164, v174, v164
	v_add_f32_e32 v220, v175, v164
	v_mov_b32_e32 v221, v220
	v_cvt_pk_bf16_f32 v164, v110, v111
	v_cvt_pk_bf16_f32 v165, v108, v109
	v_cvt_pk_bf16_f32 v166, v106, v107
	v_cvt_pk_bf16_f32 v167, v72, v73
	v_cvt_pk_bf16_f32 v176, v66, v67
	v_cvt_pk_bf16_f32 v177, v64, v65
	v_cvt_pk_bf16_f32 v178, v68, v69
	v_cvt_pk_bf16_f32 v179, v70, v71
	v_cvt_pk_bf16_f32 v228, v225, v227
	v_cvt_pk_bf16_f32 v229, v196, v197
	v_cvt_pk_bf16_f32 v230, v222, v223
	v_cvt_pk_bf16_f32 v231, v224, v226
	v_cvt_pk_bf16_f32 v222, v170, v171
	v_cvt_pk_bf16_f32 v223, v168, v169
	v_cvt_pk_bf16_f32 v224, v172, v173
	s_nop 1
	v_permlane32_swap_b32_e32 v220, v221
	v_cvt_pk_bf16_f32 v225, v174, v175
	v_permlane32_swap_b32_e32 v222, v224
	v_permlane32_swap_b32_e32 v164, v166
	v_permlane32_swap_b32_e32 v165, v167
	v_permlane32_swap_b32_e32 v176, v178
	v_permlane32_swap_b32_e32 v177, v179
	v_permlane32_swap_b32_e32 v228, v230
	v_permlane32_swap_b32_e32 v229, v231
	v_permlane32_swap_b32_e32 v223, v225
; #define SBAR() __builtin_amdgcn_sched_barrier(0)
; template <int OFF> DI s16x4 tr_read(int vb) { s16x4 r; asm volatile("ds_read_b64_tr_b16 %0, %1 offset:%2" : "=&v"(r) : "v"(vb), "i"(OFF) : "memory"); return r; }
; template <bool BAND> DI void partialSM(f32x16& p0, f32x16& p1, float& m_reg, float& mn, float& alpha, bool masked, const LAS float* tb, float C) {
;     ...
;   float pmax = p0[0];
; #pragma unroll
;   for (int r = 1; r < 16; ++r) pmax = fmaxf(pmax, p0[r]);
; #pragma unroll
;   for (int r = 0; r < 16; ++r) pmax = fmaxf(pmax, p1[r]);
;   { auto rr = __builtin_amdgcn_permlane32_swap(__float_as_uint(pmax), __float_as_uint(pmax), false, false);
;     pmax = fmaxf(__uint_as_float(rr[0]), __uint_as_float(rr[1])); }
;   if (__builtin_expect(__all(pmax - m_reg <= THRP), 1)) { mn = m_reg; alpha = 1.f; }
;   else { mn = fmaxf(m_reg, pmax); alpha = __builtin_amdgcn_exp2f((m_reg - mn) * CC); m_reg = mn; }
; template <int D0> DI void pv_one(f32x16& od, int vb, bf16x8 pa0, bf16x8 pa1, bf16x8 pa2, bf16x8 pa3) {
;   const s16x4 l0 = tr_read<v_rd_off(D0, 0, 0)>(vb), h0 = tr_read<v_rd_off(D0, 0, 1)>(vb), l1 = tr_read<v_rd_off(D0, 1, 0)>(vb), h1 = tr_read<v_rd_off(D0, 1, 1)>(vb);
;   const s16x4 l2 = tr_read<v_rd_off(D0, 2, 0)>(vb), h2 = tr_read<v_rd_off(D0, 2, 1)>(vb), l3 = tr_read<v_rd_off(D0, 3, 0)>(vb), h3 = tr_read<v_rd_off(D0, 3, 1)>(vb);
;   asm volatile("s_waitcnt lgkmcnt(0)" ::: "memory"); SBAR();
;     ...
;   od = __builtin_amdgcn_mfma_f32_32x32x16_bf16(pa0, PK(l0, h0), od, 0, 0, 0);
;   od = __builtin_amdgcn_mfma_f32_32x32x16_bf16(pa1, PK(l1, h1), od, 0, 0, 0);
;   od = __builtin_amdgcn_mfma_f32_32x32x16_bf16(pa2, PK(l2, h2), od, 0, 0, 0);
;   od = __builtin_amdgcn_mfma_f32_32x32x16_bf16(pa3, PK(l3, h3), od, 0, 0, 0);
;     ...
; }
; DI void pv_d0(f32x16* o, int vb, bf16x8 pa0, bf16x8 pa1, bf16x8 pa2, bf16x8 pa3) {
;   pv_one<0>(o[0], vb, pa0, pa1, pa2, pa3); pv_one<1>(o[1], vb, pa0, pa1, pa2, pa3); pv_one<2>(o[2], vb, pa0, pa1, pa2, pa3); pv_one<3>(o[3], vb, pa0, pa1, pa2, pa3);
.Lqsmb_join:
	s_min_i32 s62, s39, s33
	s_lshl_b64 s[16:17], s[62:63], 19
	s_add_u32 s22, s12, s16
	s_addc_u32 s23, s13, s17
	s_add_u32 s16, s14, s16
	s_addc_u32 s17, s15, s17
	v_lshl_add_u64 v[64:65], s[16:17], 0, v[112:113]
	v_lshl_add_u64 v[68:69], s[16:17], 0, v[114:115]
	v_lshl_add_u64 v[72:73], s[22:23], 0, v[112:113]
	s_lshl_b64 s[16:17], s[62:63], 13
	global_load_dwordx4 v[64:67], v[64:65], off
	s_nop 0
	global_load_dwordx4 v[68:71], v[68:69], off
	v_lshl_add_u64 v[110:111], s[22:23], 0, v[114:115]
	global_load_dwordx4 v[106:109], v[72:73], off
	global_load_dwordx4 v[168:171], v[110:111], off
	v_lshl_add_u64 v[72:73], v[192:193], 0, s[16:17]
	global_load_dwordx4 v[172:175], v[72:73], off
	s_add_i32 vcc_lo, s37, -1
	s_cmp_gt_i32 s34, vcc_lo
	s_cbranch_scc1 .Lpvmb_skip
	s_cmp_gt_i32 vcc_lo, s21
	s_cbranch_scc1 .Lpvmb_skip
	ds_read_b64_tr_b16 v[232:233], v216 offset:0
	ds_read_b64_tr_b16 v[234:235], v216 offset:0x800
	ds_read_b64_tr_b16 v[242:243], v216 offset:0x1000
	ds_read_b64_tr_b16 v[244:245], v216 offset:0x1800
	ds_read_b64_tr_b16 v[246:247], v216 offset:0x2000
	ds_read_b64_tr_b16 v[248:249], v216 offset:0x2800
	ds_read_b64_tr_b16 v[212:213], v216 offset:0x3000
	ds_read_b64_tr_b16 v[214:215], v216 offset:0x3800
	s_waitcnt lgkmcnt(0)
	s_nop 0
	v_mfma_f32_32x32x16_bf16 v[0:15], v[164:167], v[232:235], v[0:15]
	v_mfma_f32_32x32x16_bf16 v[0:15], v[176:179], v[242:245], v[0:15]
	v_mfma_f32_32x32x16_bf16 v[0:15], v[228:231], v[246:249], v[0:15]
	v_mfma_f32_32x32x16_bf16 v[0:15], v[222:225], v[212:215], v[0:15]
	ds_read_b64_tr_b16 v[212:213], v216 offset:0x200
	ds_read_b64_tr_b16 v[214:215], v216 offset:0xa00
	ds_read_b64_tr_b16 v[232:233], v216 offset:0x1200
	ds_read_b64_tr_b16 v[234:235], v216 offset:0x1a00
	ds_read_b64_tr_b16 v[242:243], v216 offset:0x2200
	ds_read_b64_tr_b16 v[244:245], v216 offset:0x2a00
	ds_read_b64_tr_b16 v[246:247], v216 offset:0x3200
	ds_read_b64_tr_b16 v[248:249], v216 offset:0x3a00
	s_waitcnt lgkmcnt(0)
	s_nop 0
	v_mfma_f32_32x32x16_bf16 v[48:63], v[164:167], v[212:215], v[48:63]
	ds_read_b64_tr_b16 v[212:213], v216 offset:0x400
	ds_read_b64_tr_b16 v[214:215], v216 offset:0xc00
	v_mfma_f32_32x32x16_bf16 v[48:63], v[176:179], v[232:235], v[48:63]
	ds_read_b64_tr_b16 v[232:233], v216 offset:0x1400
	ds_read_b64_tr_b16 v[234:235], v216 offset:0x1c00
	v_mfma_f32_32x32x16_bf16 v[48:63], v[228:231], v[242:245], v[48:63]
	ds_read_b64_tr_b16 v[242:243], v216 offset:0x2400
	ds_read_b64_tr_b16 v[244:245], v216 offset:0x2c00
	v_mfma_f32_32x32x16_bf16 v[48:63], v[222:225], v[246:249], v[48:63]
	ds_read_b64_tr_b16 v[246:247], v216 offset:0x3400
	ds_read_b64_tr_b16 v[248:249], v216 offset:0x3c00
	s_waitcnt lgkmcnt(0)
	v_mfma_f32_32x32x16_bf16 v[32:47], v[164:167], v[212:215], v[32:47]
	ds_read_b64_tr_b16 v[212:213], v216 offset:0x600
	ds_read_b64_tr_b16 v[214:215], v216 offset:0xe00
	v_mfma_f32_32x32x16_bf16 v[32:47], v[176:179], v[232:235], v[32:47]
	ds_read_b64_tr_b16 v[232:233], v216 offset:0x1600
	ds_read_b64_tr_b16 v[234:235], v216 offset:0x1e00
	v_mfma_f32_32x32x16_bf16 v[32:47], v[228:231], v[242:245], v[32:47]
	ds_read_b64_tr_b16 v[242:243], v216 offset:0x2600
	ds_read_b64_tr_b16 v[244:245], v216 offset:0x2e00
	v_mfma_f32_32x32x16_bf16 v[32:47], v[222:225], v[246:249], v[32:47]
	ds_read_b64_tr_b16 v[246:247], v216 offset:0x3600
	ds_read_b64_tr_b16 v[248:249], v216 offset:0x3e00
	s_waitcnt lgkmcnt(0)
	v_mfma_f32_32x32x16_bf16 v[16:31], v[164:167], v[212:215], v[16:31]
	s_cmp_gt_i32 s34, s37
	s_cselect_b64 s[16:17], -1, 0
	s_cmp_gt_i32 s37, s21
	s_cselect_b64 s[22:23], -1, 0
	s_or_b64 vcc, s[16:17], s[22:23]
	v_cndmask_b32_e32 v74, v74, v211, vcc
	v_cndmask_b32_e32 v75, v75, v211, vcc
	v_mfma_f32_32x32x16_bf16 v[16:31], v[176:179], v[232:235], v[16:31]
	v_cndmask_b32_e32 v72, v104, v211, vcc
	v_cndmask_b32_e32 v73, v105, v211, vcc
	v_cndmask_b32_e32 v104, v102, v211, vcc
	v_cndmask_b32_e32 v102, v103, v211, vcc
	v_max_f32_e32 v103, v75, v75
	v_max_f32_e32 v105, v74, v74
	v_cndmask_b32_e32 v76, v76, v211, vcc
	v_cndmask_b32_e32 v77, v77, v211, vcc
	v_max_f32_e32 v103, v105, v103
	v_cndmask_b32_e32 v78, v78, v211, vcc
	v_cndmask_b32_e32 v79, v79, v211, vcc
	v_max3_f32 v103, v103, v76, v77
	v_cndmask_b32_e32 v80, v80, v211, vcc
	v_cndmask_b32_e32 v81, v81, v211, vcc
	v_max3_f32 v103, v103, v78, v79
	v_cndmask_b32_e32 v82, v82, v211, vcc
	v_cndmask_b32_e32 v83, v83, v211, vcc
	v_max3_f32 v103, v103, v80, v81
	v_cndmask_b32_e32 v84, v84, v211, vcc
	v_cndmask_b32_e32 v85, v85, v211, vcc
	v_max3_f32 v103, v103, v82, v83
	v_cndmask_b32_e32 v86, v86, v211, vcc
	v_cndmask_b32_e32 v87, v87, v211, vcc
	v_max3_f32 v103, v103, v84, v85
	v_cndmask_b32_e32 v88, v88, v211, vcc
	v_cndmask_b32_e32 v89, v89, v211, vcc
	v_max3_f32 v103, v103, v86, v87
	v_mfma_f32_32x32x16_bf16 v[16:31], v[228:231], v[242:245], v[16:31]
	v_cndmask_b32_e32 v90, v90, v211, vcc
	v_cndmask_b32_e32 v91, v91, v211, vcc
	v_max3_f32 v103, v103, v88, v89
	v_cndmask_b32_e32 v92, v92, v211, vcc
	v_cndmask_b32_e32 v93, v93, v211, vcc
	v_max3_f32 v103, v103, v90, v91
	v_cndmask_b32_e32 v94, v94, v211, vcc
	v_cndmask_b32_e32 v95, v95, v211, vcc
	v_max3_f32 v103, v103, v92, v93
	v_cndmask_b32_e32 v96, v96, v211, vcc
	v_cndmask_b32_e32 v97, v97, v211, vcc
	v_max3_f32 v103, v103, v94, v95
	v_cndmask_b32_e32 v98, v98, v211, vcc
	v_cndmask_b32_e32 v99, v99, v211, vcc
	v_max3_f32 v103, v103, v96, v97
	v_cndmask_b32_e32 v100, v100, v211, vcc
	v_cndmask_b32_e32 v101, v101, v211, vcc
	v_max3_f32 v103, v103, v98, v99
	v_max3_f32 v103, v103, v100, v101
	v_max3_f32 v103, v103, v104, v102
	v_mfma_f32_32x32x16_bf16 v[16:31], v[222:225], v[246:249], v[16:31]
	v_max3_f32 v103, v103, v72, v73
	v_mov_b32_e32 v105, v103
	s_nop 1
	v_permlane32_swap_b32_e32 v103, v105
	v_max_f32_e32 v105, v105, v105
	v_max_f32_e32 v103, v103, v103
	v_max_f32_e32 v103, v103, v105
	v_sub_f32_e32 v105, v103, v203
	v_cmp_ge_f32_e32 vcc, s84, v105
	v_mov_b32_e32 v222, 1.0
	s_cmp_eq_u64 vcc, exec
.Lpvmb_join:
	s_cbranch_scc0 .LBB0_356

; #define LAS __attribute__((address_space(3)))
; template <bool BAND> DI void partialSM(f32x16& p0, f32x16& p1, float& m_reg, float& mn, float& alpha, bool masked, const LAS float* tb, float C) {
;     ...
;   const float mnC = -mn * CC;
; #pragma unroll
;   for (int r = 0; r < 16; ++r) p0[r] = fmaf(p0[r], CC, mnC);
; #pragma unroll
;   for (int r = 0; r < 16; ++r) p1[r] = fmaf(p1[r], CC, mnC);
; #pragma unroll
;   for (int r = 0; r < 16; ++r) p0[r] = __builtin_amdgcn_exp2f(p0[r]);
; }
; DI void finishSM(f32x16& p0, f32x16& p1, float alpha, float& l_reg, bf16x8& pa0, bf16x8& pa1, bf16x8& pa2, bf16x8& pa3) {
; #pragma unroll
;   for (int r = 0; r < 16; ++r) p1[r] = __builtin_amdgcn_exp2f(p1[r]);
;   float ps = 0;
; #pragma unroll
;   for (int r = 0; r < 16; ++r) ps += p0[r];
; #pragma unroll
;   for (int r = 0; r < 16; ++r) ps += p1[r];
;   { auto rr = __builtin_amdgcn_permlane32_swap(__float_as_uint(ps), __float_as_uint(ps), false, false);
;     ps = __uint_as_float(rr[0]) + __uint_as_float(rr[1]); }
;   l_reg = l_reg * alpha + ps;
;     ...
;   PK4(p0, 0, pa0); PK4(p0, 8, pa1); PK4(p1, 0, pa2); PK4(p1, 8, pa3);
;     ...
; }
; template <int NQ> DI void qkt(f32x16& p0, f32x16& p1, const LAS char* Ks, const LAS char* KRs, const bf16x8* qr, int r32, int hi) {
;   p0 = f32x16{}; p1 = f32x16{};
; #pragma unroll
;   for (int d0 = 0; d0 < 8; ++d0) { const int cb = (d0 * 16 + hi * 8) * 2;
;     const bf16x8 b0 = *(const LAS bf16x8*)(Ks + KSWZ(r32, cb));
;     const bf16x8 b1 = *(const LAS bf16x8*)(Ks + KSWZ(32 + r32, cb));
;     p0 = __builtin_amdgcn_mfma_f32_32x32x16_bf16(b0, qr[d0], p0, 0, 0, 0);
;     p1 = __builtin_amdgcn_mfma_f32_32x32x16_bf16(b1, qr[d0], p1, 0, 0, 0); }
;   if (NQ == 12) {
; #pragma unroll
;     for (int d0 = 0; d0 < 4; ++d0) { const int cb = (d0 * 16 + hi * 8) * 2;
;       const bf16x8 b0 = *(const LAS bf16x8*)(KRs + KRSWZ(r32, cb));
;       const bf16x8 b1 = *(const LAS bf16x8*)(KRs + KRSWZ(32 + r32, cb));
;       p0 = __builtin_amdgcn_mfma_f32_32x32x16_bf16(b0, qr[8 + d0], p0, 0, 0, 0);
;       p1 = __builtin_amdgcn_mfma_f32_32x32x16_bf16(b1, qr[8 + d0], p1, 0, 0, 0); }
;   }
.LBB0_349:
	v_mul_f32_e32 v176, 0xbdd53b94, v203
	v_fmamk_f32 v64, v74, 0x3dd53b94, v176
	v_fmamk_f32 v65, v75, 0x3dd53b94, v176
	v_fmamk_f32 v66, v76, 0x3dd53b94, v176
	v_fmamk_f32 v67, v77, 0x3dd53b94, v176
	v_fmamk_f32 v68, v78, 0x3dd53b94, v176
	v_fmamk_f32 v69, v79, 0x3dd53b94, v176
	v_fmamk_f32 v70, v80, 0x3dd53b94, v176
	v_fmamk_f32 v71, v81, 0x3dd53b94, v176
	v_fmamk_f32 v74, v82, 0x3dd53b94, v176
	v_fmamk_f32 v75, v83, 0x3dd53b94, v176
	v_fmamk_f32 v76, v84, 0x3dd53b94, v176
	v_fmamk_f32 v77, v85, 0x3dd53b94, v176
	v_fmamk_f32 v78, v86, 0x3dd53b94, v176
	v_fmamk_f32 v79, v87, 0x3dd53b94, v176
	v_fmamk_f32 v80, v88, 0x3dd53b94, v176
	v_fmamk_f32 v81, v89, 0x3dd53b94, v176
	v_fmamk_f32 v167, v96, 0x3dd53b94, v176
	v_fmamk_f32 v168, v97, 0x3dd53b94, v176
	v_fmamk_f32 v169, v98, 0x3dd53b94, v176
	v_fmamk_f32 v170, v99, 0x3dd53b94, v176
	v_fmamk_f32 v171, v100, 0x3dd53b94, v176
	v_fmamk_f32 v172, v101, 0x3dd53b94, v176
	v_fmamk_f32 v165, v104, 0x3dd53b94, v176
	v_exp_f32_e32 v110, v64
	v_exp_f32_e32 v164, v65
	v_exp_f32_e32 v108, v66
	v_exp_f32_e32 v111, v67
	v_exp_f32_e32 v107, v68
	v_exp_f32_e32 v109, v69
	v_exp_f32_e32 v105, v70
	v_exp_f32_e32 v106, v71
	v_exp_f32_e32 v101, v74
	v_exp_f32_e32 v104, v75
	v_exp_f32_e32 v100, v76
	v_exp_f32_e32 v103, v77
	v_exp_f32_e32 v97, v78
	v_exp_f32_e32 v99, v79
	v_exp_f32_e32 v96, v80
	v_exp_f32_e32 v98, v81
	v_fmamk_f32 v177, v93, 0x3dd53b94, v176
	v_fmamk_f32 v166, v95, 0x3dd53b94, v176
	v_fmamk_f32 v102, v102, 0x3dd53b94, v176
	v_fmamk_f32 v173, v90, 0x3dd53b94, v176
	v_fmamk_f32 v174, v91, 0x3dd53b94, v176
	v_fmamk_f32 v175, v92, 0x3dd53b94, v176
	v_fmamk_f32 v179, v94, 0x3dd53b94, v176
	v_fmamk_f32 v196, v72, 0x3dd53b94, v176
	v_fmamk_f32 v197, v73, 0x3dd53b94, v176
	s_waitcnt lgkmcnt(0)
	s_barrier
	s_cmp_gt_i32 s34, s39
	s_cbranch_scc1 .Lqsma_skip
	s_cmp_ge_i32 s37, s21
	s_cbranch_scc1 .Lqsma_skip
	ds_read_b128 v[80:83], v207 offset:41472
	ds_read_b128 v[64:67], v207 offset:32768
	ds_read_b128 v[212:215], v207 offset:32800
	ds_read_b128 v[224:227], v207 offset:41504
	v_exp_f32_e32 v177, v177
	s_waitcnt lgkmcnt(3)
	v_mfma_f32_32x32x16_bf16 v[80:95], v[80:83], v[160:163], 0
	v_exp_f32_e32 v179, v179
	v_exp_f32_e32 v166, v166
	v_exp_f32_e32 v167, v167
	v_exp_f32_e32 v165, v165
	v_exp_f32_e32 v102, v102
	v_exp_f32_e32 v196, v196
	v_exp_f32_e32 v197, v197
	s_waitcnt lgkmcnt(2)
	v_mfma_f32_32x32x16_bf16 v[64:79], v[64:67], v[160:163], 0
	s_waitcnt lgkmcnt(1)
	v_mfma_f32_32x32x16_bf16 v[64:79], v[212:215], v[156:159], v[64:79]
	s_waitcnt lgkmcnt(0)
	v_mfma_f32_32x32x16_bf16 v[80:95], v[224:227], v[156:159], v[80:95]
	ds_read_b128 v[212:215], v207 offset:32832
	ds_read_b128 v[224:227], v207 offset:41536
	s_waitcnt lgkmcnt(1)
	v_mfma_f32_32x32x16_bf16 v[64:79], v[212:215], v[152:155], v[64:79]
	s_waitcnt lgkmcnt(0)
	v_mfma_f32_32x32x16_bf16 v[80:95], v[224:227], v[152:155], v[80:95]
	ds_read_b128 v[212:215], v207 offset:32864
	ds_read_b128 v[224:227], v207 offset:41568
	s_waitcnt lgkmcnt(1)
	v_mfma_f32_32x32x16_bf16 v[64:79], v[212:215], v[148:151], v[64:79]
	s_waitcnt lgkmcnt(0)
	v_mfma_f32_32x32x16_bf16 v[80:95], v[224:227], v[148:151], v[80:95]
	ds_read_b128 v[212:215], v207 offset:32896
	ds_read_b128 v[224:227], v207 offset:41600
	s_waitcnt lgkmcnt(1)
	v_mfma_f32_32x32x16_bf16 v[64:79], v[212:215], v[144:147], v[64:79]
	s_waitcnt lgkmcnt(0)
	v_mfma_f32_32x32x16_bf16 v[80:95], v[224:227], v[144:147], v[80:95]
	ds_read_b128 v[212:215], v207 offset:32928
	ds_read_b128 v[224:227], v207 offset:41632
	s_waitcnt lgkmcnt(1)
	v_mfma_f32_32x32x16_bf16 v[64:79], v[212:215], v[140:143], v[64:79]
	s_waitcnt lgkmcnt(0)
	v_mfma_f32_32x32x16_bf16 v[80:95], v[224:227], v[140:143], v[80:95]
	ds_read_b128 v[212:215], v207 offset:32960
	ds_read_b128 v[224:227], v207 offset:41664
	s_waitcnt lgkmcnt(1)
	v_mfma_f32_32x32x16_bf16 v[64:79], v[212:215], v[136:139], v[64:79]
	s_waitcnt lgkmcnt(0)
	v_mfma_f32_32x32x16_bf16 v[80:95], v[224:227], v[136:139], v[80:95]
	ds_read_b128 v[212:215], v207 offset:32992
	ds_read_b128 v[224:227], v207 offset:41696
	s_waitcnt lgkmcnt(1)
	v_mfma_f32_32x32x16_bf16 v[64:79], v[212:215], v[132:135], v[64:79]
	s_waitcnt lgkmcnt(0)
	v_mfma_f32_32x32x16_bf16 v[80:95], v[224:227], v[132:135], v[80:95]
	ds_read_b128 v[212:215], v217 offset:4608
	ds_read_b128 v[224:227], v217
	ds_read_b128 v[228:231], v217 offset:32
	s_waitcnt lgkmcnt(1)
	v_mfma_f32_32x32x16_bf16 v[64:79], v[224:227], v[128:131], v[64:79]
	v_mfma_f32_32x32x16_bf16 v[80:95], v[212:215], v[128:131], v[80:95]
	ds_read_b128 v[212:215], v217 offset:4640
	s_waitcnt lgkmcnt(1)
	v_mfma_f32_32x32x16_bf16 v[64:79], v[228:231], v[124:127], v[64:79]
	v_exp_f32_e32 v228, v172
	s_waitcnt lgkmcnt(0)
	v_mfma_f32_32x32x16_bf16 v[80:95], v[212:215], v[124:127], v[80:95]
	ds_read_b128 v[212:215], v217 offset:64
	ds_read_b128 v[224:227], v217 offset:4672
	s_waitcnt lgkmcnt(1)
	v_mfma_f32_32x32x16_bf16 v[64:79], v[212:215], v[120:123], v[64:79]
	s_waitcnt lgkmcnt(0)
	v_mfma_f32_32x32x16_bf16 v[80:95], v[224:227], v[120:123], v[80:95]
	ds_read_b128 v[212:215], v217 offset:96
	ds_read_b128 v[224:227], v217 offset:4704
	s_waitcnt lgkmcnt(1)
	v_mfma_f32_32x32x16_bf16 v[64:79], v[212:215], v[116:119], v[64:79]
	v_exp_f32_e32 v215, v168
	v_add_f32_e32 v168, 0, v110
	v_add_f32_e32 v168, v164, v168
	v_add_f32_e32 v168, v108, v168
	v_add_f32_e32 v168, v111, v168
	v_add_f32_e32 v168, v107, v168
	v_add_f32_e32 v168, v109, v168
	v_add_f32_e32 v168, v105, v168
	v_add_f32_e32 v168, v106, v168
	v_add_f32_e32 v168, v101, v168
	v_add_f32_e32 v168, v104, v168
	v_add_f32_e32 v168, v100, v168
	v_add_f32_e32 v168, v103, v168
	v_exp_f32_e32 v212, v173
	v_add_f32_e32 v168, v97, v168
	v_exp_f32_e32 v213, v174
	v_add_f32_e32 v168, v99, v168
	v_exp_f32_e32 v214, v175
	v_add_f32_e32 v168, v96, v168
	v_add_f32_e32 v168, v98, v168
	v_add_f32_e32 v168, v212, v168
	v_add_f32_e32 v168, v213, v168
	v_add_f32_e32 v168, v214, v168
	v_add_f32_e32 v168, v177, v168
	s_waitcnt lgkmcnt(0)
; DI void finishSM(f32x16& p0, f32x16& p1, float alpha, float& l_reg, bf16x8& pa0, bf16x8& pa1, bf16x8& pa2, bf16x8& pa3) {
; #pragma unroll
;   for (int r = 0; r < 16; ++r) p1[r] = __builtin_amdgcn_exp2f(p1[r]);
;   float ps = 0;
; #pragma unroll
;   for (int r = 0; r < 16; ++r) ps += p0[r];
; #pragma unroll
;   for (int r = 0; r < 16; ++r) ps += p1[r];
;   { auto rr = __builtin_amdgcn_permlane32_swap(__float_as_uint(ps), __float_as_uint(ps), false, false);
;     ps = __uint_as_float(rr[0]) + __uint_as_float(rr[1]); }
;   l_reg = l_reg * alpha + ps;
;     ...
;   PK4(p0, 0, pa0); PK4(p0, 8, pa1); PK4(p1, 0, pa2); PK4(p1, 8, pa3);
	v_mfma_f32_32x32x16_bf16 v[80:95], v[224:227], v[116:119], v[80:95]
	v_exp_f32_e32 v225, v169
	v_add_f32_e32 v168, v179, v168
	v_exp_f32_e32 v226, v170
	v_add_f32_e32 v168, v166, v168
	v_exp_f32_e32 v227, v171
	v_add_f32_e32 v168, v167, v168
	v_add_f32_e32 v168, v215, v168
	v_add_f32_e32 v168, v225, v168
	v_add_f32_e32 v168, v226, v168
	v_add_f32_e32 v168, v227, v168
	v_add_f32_e32 v168, v228, v168
	v_add_f32_e32 v168, v165, v168
	v_add_f32_e32 v168, v102, v168
	v_add_f32_e32 v168, v196, v168
	v_add_f32_e32 v223, v197, v168
	v_mov_b32_e32 v224, v223
	v_cvt_pk_bf16_f32 v168, v110, v164
	v_cvt_pk_bf16_f32 v169, v108, v111
	v_cvt_pk_bf16_f32 v170, v107, v109
	s_nop 1
	v_permlane32_swap_b32_e32 v223, v224
	v_cvt_pk_bf16_f32 v171, v105, v106
	v_permlane32_swap_b32_e32 v168, v170
	v_cvt_pk_bf16_f32 v172, v101, v104
	v_cvt_pk_bf16_f32 v173, v100, v103
	v_cvt_pk_bf16_f32 v174, v97, v99
	v_cvt_pk_bf16_f32 v175, v96, v98
	v_cvt_pk_bf16_f32 v212, v212, v213
	v_cvt_pk_bf16_f32 v213, v214, v177
	v_cvt_pk_bf16_f32 v214, v179, v166
	v_cvt_pk_bf16_f32 v215, v167, v215
	v_cvt_pk_bf16_f32 v226, v225, v226
	v_cvt_pk_bf16_f32 v227, v227, v228
	v_cvt_pk_bf16_f32 v228, v165, v102
	v_cvt_pk_bf16_f32 v229, v196, v197
	v_permlane32_swap_b32_e32 v169, v171
	v_permlane32_swap_b32_e32 v172, v174
	v_permlane32_swap_b32_e32 v173, v175
	v_permlane32_swap_b32_e32 v212, v214
	v_permlane32_swap_b32_e32 v213, v215
	v_permlane32_swap_b32_e32 v226, v228
	v_permlane32_swap_b32_e32 v227, v229
; #define SBAR() __builtin_amdgcn_sched_barrier(0)
; template <int OFF> DI s16x4 tr_read(int vb) { s16x4 r; asm volatile("ds_read_b64_tr_b16 %0, %1 offset:%2" : "=&v"(r) : "v"(vb), "i"(OFF) : "memory"); return r; }
; template <bool BAND> DI void partialSM(f32x16& p0, f32x16& p1, float& m_reg, float& mn, float& alpha, bool masked, const LAS float* tb, float C) {
;     ...
;   float pmax = p0[0];
; #pragma unroll
;   for (int r = 1; r < 16; ++r) pmax = fmaxf(pmax, p0[r]);
; #pragma unroll
;   for (int r = 0; r < 16; ++r) pmax = fmaxf(pmax, p1[r]);
;   { auto rr = __builtin_amdgcn_permlane32_swap(__float_as_uint(pmax), __float_as_uint(pmax), false, false);
;     pmax = fmaxf(__uint_as_float(rr[0]), __uint_as_float(rr[1])); }
;   if (__builtin_expect(__all(pmax - m_reg <= THRP), 1)) { mn = m_reg; alpha = 1.f; }
;   else { mn = fmaxf(m_reg, pmax); alpha = __builtin_amdgcn_exp2f((m_reg - mn) * CC); m_reg = mn; }
; template <int D0> DI void pv_one(f32x16& od, int vb, bf16x8 pa0, bf16x8 pa1, bf16x8 pa2, bf16x8 pa3) {
;   const s16x4 l0 = tr_read<v_rd_off(D0, 0, 0)>(vb), h0 = tr_read<v_rd_off(D0, 0, 1)>(vb), l1 = tr_read<v_rd_off(D0, 1, 0)>(vb), h1 = tr_read<v_rd_off(D0, 1, 1)>(vb);
;   const s16x4 l2 = tr_read<v_rd_off(D0, 2, 0)>(vb), h2 = tr_read<v_rd_off(D0, 2, 1)>(vb), l3 = tr_read<v_rd_off(D0, 3, 0)>(vb), h3 = tr_read<v_rd_off(D0, 3, 1)>(vb);
;   asm volatile("s_waitcnt lgkmcnt(0)" ::: "memory"); SBAR();
;     ...
;   od = __builtin_amdgcn_mfma_f32_32x32x16_bf16(pa0, PK(l0, h0), od, 0, 0, 0);
;   od = __builtin_amdgcn_mfma_f32_32x32x16_bf16(pa1, PK(l1, h1), od, 0, 0, 0);
;   od = __builtin_amdgcn_mfma_f32_32x32x16_bf16(pa2, PK(l2, h2), od, 0, 0, 0);
;   od = __builtin_amdgcn_mfma_f32_32x32x16_bf16(pa3, PK(l3, h3), od, 0, 0, 0);
;     ...
; }
; DI void pv_d0(f32x16* o, int vb, bf16x8 pa0, bf16x8 pa1, bf16x8 pa2, bf16x8 pa3) {
;   pv_one<0>(o[0], vb, pa0, pa1, pa2, pa3); pv_one<1>(o[1], vb, pa0, pa1, pa2, pa3); pv_one<2>(o[2], vb, pa0, pa1, pa2, pa3); pv_one<3>(o[3], vb, pa0, pa1, pa2, pa3);
.Lqsma_join:
	s_min_i32 s16, s35, s33
	s_ashr_i32 s17, s16, 31
	s_lshl_b64 s[22:23], s[16:17], 19
	s_add_u32 s40, s12, s22
	s_addc_u32 s41, s13, s23
	s_add_u32 s22, s14, s22
	s_addc_u32 s23, s15, s23
	s_lshl_b64 s[16:17], s[16:17], 13
	v_lshl_add_u64 v[96:97], s[22:23], 0, v[112:113]
	v_lshl_add_u64 v[100:101], s[22:23], 0, v[114:115]
	v_lshl_add_u64 v[104:105], s[40:41], 0, v[112:113]
	v_lshl_add_u64 v[108:109], s[40:41], 0, v[114:115]
	v_lshl_add_u64 v[164:165], v[192:193], 0, s[16:17]
	global_load_dwordx4 v[96:99], v[96:97], off
	s_nop 0
	global_load_dwordx4 v[100:103], v[100:101], off
	s_nop 0
	global_load_dwordx4 v[104:107], v[104:105], off
	s_nop 0
	global_load_dwordx4 v[108:111], v[108:109], off
	s_nop 0
	global_load_dwordx4 v[164:167], v[164:165], off
	s_cmp_gt_i32 s34, s37
	s_cbranch_scc1 .Lpvma_skip
	s_cmp_gt_i32 s37, s21
	s_cbranch_scc1 .Lpvma_skip
	ds_read_b64_tr_b16 v[230:231], v202 offset:0
	ds_read_b64_tr_b16 v[232:233], v202 offset:0x800
	ds_read_b64_tr_b16 v[234:235], v202 offset:0x1000
	ds_read_b64_tr_b16 v[236:237], v202 offset:0x1800
	ds_read_b64_tr_b16 v[242:243], v202 offset:0x2000
	ds_read_b64_tr_b16 v[244:245], v202 offset:0x2800
	ds_read_b64_tr_b16 v[246:247], v202 offset:0x3000
	ds_read_b64_tr_b16 v[248:249], v202 offset:0x3800
	s_waitcnt lgkmcnt(0)
	s_nop 0
	v_mfma_f32_32x32x16_bf16 v[0:15], v[168:171], v[230:233], v[0:15]
	ds_read_b64_tr_b16 v[230:231], v202 offset:0x200
	ds_read_b64_tr_b16 v[232:233], v202 offset:0xa00
	v_mfma_f32_32x32x16_bf16 v[0:15], v[172:175], v[234:237], v[0:15]
	ds_read_b64_tr_b16 v[234:235], v202 offset:0x1200
	ds_read_b64_tr_b16 v[236:237], v202 offset:0x1a00
	v_mfma_f32_32x32x16_bf16 v[0:15], v[212:215], v[242:245], v[0:15]
	ds_read_b64_tr_b16 v[242:243], v202 offset:0x2200
	ds_read_b64_tr_b16 v[244:245], v202 offset:0x2a00
	v_mfma_f32_32x32x16_bf16 v[0:15], v[226:229], v[246:249], v[0:15]
	ds_read_b64_tr_b16 v[246:247], v202 offset:0x3200
	ds_read_b64_tr_b16 v[248:249], v202 offset:0x3a00
	s_waitcnt lgkmcnt(0)
	v_mfma_f32_32x32x16_bf16 v[48:63], v[168:171], v[230:233], v[48:63]
	ds_read_b64_tr_b16 v[230:231], v202 offset:0x400
	ds_read_b64_tr_b16 v[232:233], v202 offset:0xc00
	v_mfma_f32_32x32x16_bf16 v[48:63], v[172:175], v[234:237], v[48:63]
	ds_read_b64_tr_b16 v[234:235], v202 offset:0x1400
	ds_read_b64_tr_b16 v[236:237], v202 offset:0x1c00
	v_mfma_f32_32x32x16_bf16 v[48:63], v[212:215], v[242:245], v[48:63]
	ds_read_b64_tr_b16 v[242:243], v202 offset:0x2400
	ds_read_b64_tr_b16 v[244:245], v202 offset:0x2c00
	v_mfma_f32_32x32x16_bf16 v[48:63], v[226:229], v[246:249], v[48:63]
	ds_read_b64_tr_b16 v[246:247], v202 offset:0x3400
	ds_read_b64_tr_b16 v[248:249], v202 offset:0x3c00
	s_waitcnt lgkmcnt(0)
	v_mfma_f32_32x32x16_bf16 v[32:47], v[168:171], v[230:233], v[32:47]
	ds_read_b64_tr_b16 v[230:231], v202 offset:0x600
	ds_read_b64_tr_b16 v[232:233], v202 offset:0xe00
	v_mfma_f32_32x32x16_bf16 v[32:47], v[172:175], v[234:237], v[32:47]
	ds_read_b64_tr_b16 v[234:235], v202 offset:0x1600
	ds_read_b64_tr_b16 v[236:237], v202 offset:0x1e00
	v_mfma_f32_32x32x16_bf16 v[32:47], v[212:215], v[242:245], v[32:47]
	ds_read_b64_tr_b16 v[242:243], v202 offset:0x2600
	ds_read_b64_tr_b16 v[244:245], v202 offset:0x2e00
	v_mfma_f32_32x32x16_bf16 v[32:47], v[226:229], v[246:249], v[32:47]
	ds_read_b64_tr_b16 v[246:247], v202 offset:0x3600
	ds_read_b64_tr_b16 v[248:249], v202 offset:0x3e00
	s_waitcnt lgkmcnt(0)
	v_mfma_f32_32x32x16_bf16 v[16:31], v[168:171], v[230:233], v[16:31]
	s_cmp_gt_i32 s34, s39
	s_cselect_b64 s[16:17], -1, 0
	s_cmp_ge_i32 s37, s21
	s_cselect_b64 s[22:23], -1, 0
	s_or_b64 vcc, s[16:17], s[22:23]
	v_cndmask_b32_e32 v65, v65, v211, vcc
	v_cndmask_b32_e32 v64, v64, v211, vcc
	v_mfma_f32_32x32x16_bf16 v[16:31], v[172:175], v[234:237], v[16:31]
	v_max_f32_e32 v168, v65, v65
	v_max_f32_e32 v169, v64, v64
	v_cndmask_b32_e32 v67, v67, v211, vcc
	v_cndmask_b32_e32 v66, v66, v211, vcc
	v_max_f32_e32 v168, v169, v168
	v_cndmask_b32_e32 v69, v69, v211, vcc
	v_cndmask_b32_e32 v68, v68, v211, vcc
	v_max3_f32 v168, v168, v66, v67
	v_cndmask_b32_e32 v71, v71, v211, vcc
	v_cndmask_b32_e32 v70, v70, v211, vcc
	v_max3_f32 v168, v168, v68, v69
	v_cndmask_b32_e32 v73, v73, v211, vcc
	v_cndmask_b32_e32 v72, v72, v211, vcc
	v_max3_f32 v168, v168, v70, v71
	v_cndmask_b32_e32 v75, v75, v211, vcc
	v_cndmask_b32_e32 v74, v74, v211, vcc
	v_max3_f32 v168, v168, v72, v73
	v_cndmask_b32_e32 v77, v77, v211, vcc
	v_cndmask_b32_e32 v76, v76, v211, vcc
	v_max3_f32 v168, v168, v74, v75
	v_cndmask_b32_e32 v79, v79, v211, vcc
	v_cndmask_b32_e32 v78, v78, v211, vcc
	v_max3_f32 v168, v168, v76, v77
	v_mfma_f32_32x32x16_bf16 v[16:31], v[212:215], v[242:245], v[16:31]
	v_cndmask_b32_e32 v81, v81, v211, vcc
	v_cndmask_b32_e32 v80, v80, v211, vcc
	v_max3_f32 v168, v168, v78, v79
	v_cndmask_b32_e32 v83, v83, v211, vcc
	v_cndmask_b32_e32 v82, v82, v211, vcc
	v_max3_f32 v168, v168, v80, v81
	v_cndmask_b32_e32 v85, v85, v211, vcc
	v_cndmask_b32_e32 v84, v84, v211, vcc
	v_max3_f32 v168, v168, v82, v83
	v_cndmask_b32_e32 v87, v87, v211, vcc
	v_cndmask_b32_e32 v86, v86, v211, vcc
	v_max3_f32 v168, v168, v84, v85
	v_cndmask_b32_e32 v89, v89, v211, vcc
	v_cndmask_b32_e32 v88, v88, v211, vcc
	v_max3_f32 v168, v168, v86, v87
	v_cndmask_b32_e32 v91, v91, v211, vcc
	v_cndmask_b32_e32 v90, v90, v211, vcc
	v_max3_f32 v168, v168, v88, v89
	v_cndmask_b32_e32 v93, v93, v211, vcc
	v_cndmask_b32_e32 v92, v92, v211, vcc
	v_max3_f32 v168, v168, v90, v91
	v_cndmask_b32_e32 v95, v95, v211, vcc
	v_cndmask_b32_e32 v94, v94, v211, vcc
	v_max3_f32 v168, v168, v92, v93
	v_mfma_f32_32x32x16_bf16 v[16:31], v[226:229], v[246:249], v[16:31]
	v_max3_f32 v168, v168, v94, v95
	v_mov_b32_e32 v169, v168
	s_nop 1
	v_permlane32_swap_b32_e32 v168, v169
	v_max_f32_e32 v169, v169, v169
	v_max_f32_e32 v168, v168, v168
	v_max_f32_e32 v168, v168, v169
	v_sub_f32_e32 v169, v168, v203
	v_cmp_ge_f32_e32 vcc, s84, v169
	v_mov_b32_e32 v177, 1.0
	s_cmp_eq_u64 vcc, exec

; DI void finishSM(f32x16& p0, f32x16& p1, float alpha, float& l_reg, bf16x8& pa0, bf16x8& pa1, bf16x8& pa2, bf16x8& pa3) {
; #pragma unroll
;   for (int r = 0; r < 16; ++r) p1[r] = __builtin_amdgcn_exp2f(p1[r]);
;   float ps = 0;
; #pragma unroll
;   for (int r = 0; r < 16; ++r) ps += p0[r];
; #pragma unroll
;   for (int r = 0; r < 16; ++r) ps += p1[r];
;   { auto rr = __builtin_amdgcn_permlane32_swap(__float_as_uint(ps), __float_as_uint(ps), false, false);
;     ps = __uint_as_float(rr[0]) + __uint_as_float(rr[1]); }
;   l_reg = l_reg * alpha + ps;
;     ...
;   PK4(p0, 0, pa0); PK4(p0, 8, pa1); PK4(p1, 0, pa2); PK4(p1, 8, pa3);
.Lqsmb_skip:
	v_exp_f32_e32 v170, v170
	v_exp_f32_e32 v171, v171
	v_exp_f32_e32 v168, v168
	v_exp_f32_e32 v169, v169
	v_exp_f32_e32 v222, v174
	v_exp_f32_e32 v174, v164
	v_add_f32_e32 v164, 0, v110
	v_add_f32_e32 v164, v111, v164
	v_add_f32_e32 v164, v108, v164
	v_add_f32_e32 v164, v109, v164
	v_add_f32_e32 v164, v106, v164
	v_add_f32_e32 v164, v107, v164
	v_add_f32_e32 v164, v72, v164
	v_add_f32_e32 v164, v73, v164
	v_add_f32_e32 v164, v66, v164
	v_add_f32_e32 v164, v67, v164
	v_add_f32_e32 v164, v64, v164
	v_add_f32_e32 v164, v65, v164
	v_exp_f32_e32 v225, v196
	v_add_f32_e32 v164, v68, v164
	v_exp_f32_e32 v227, v197
	v_add_f32_e32 v164, v69, v164
	v_exp_f32_e32 v196, v178
	v_add_f32_e32 v164, v70, v164
	v_exp_f32_e32 v197, v179
	v_add_f32_e32 v164, v71, v164
	v_add_f32_e32 v164, v225, v164
	v_exp_f32_e32 v223, v175
	v_add_f32_e32 v164, v227, v164
	v_exp_f32_e32 v224, v172
	v_add_f32_e32 v164, v196, v164
	v_exp_f32_e32 v226, v173
	v_add_f32_e32 v164, v197, v164
	v_add_f32_e32 v164, v222, v164
	v_add_f32_e32 v164, v223, v164
	v_add_f32_e32 v164, v224, v164
	v_add_f32_e32 v164, v226, v164
	v_exp_f32_e32 v172, v166
	v_add_f32_e32 v164, v170, v164
	v_exp_f32_e32 v173, v167
	v_add_f32_e32 v164, v171, v164
	v_add_f32_e32 v164, v168, v164
	v_exp_f32_e32 v175, v165
	v_add_f32_e32 v164, v169, v164
	v_add_f32_e32 v164, v172, v164
	v_add_f32_e32 v164, v173, v164
	v_add_f32_e32 v164, v174, v164
	v_add_f32_e32 v220, v175, v164
	v_mov_b32_e32 v221, v220
	v_cvt_pk_bf16_f32 v164, v110, v111
	v_cvt_pk_bf16_f32 v165, v108, v109
	v_cvt_pk_bf16_f32 v166, v106, v107
	v_cvt_pk_bf16_f32 v167, v72, v73
	v_cvt_pk_bf16_f32 v176, v66, v67
	v_cvt_pk_bf16_f32 v177, v64, v65
	v_cvt_pk_bf16_f32 v178, v68, v69
	v_cvt_pk_bf16_f32 v179, v70, v71
	v_cvt_pk_bf16_f32 v228, v225, v227
	v_cvt_pk_bf16_f32 v229, v196, v197
	v_cvt_pk_bf16_f32 v230, v222, v223
	v_cvt_pk_bf16_f32 v231, v224, v226
	v_cvt_pk_bf16_f32 v222, v170, v171
	v_cvt_pk_bf16_f32 v223, v168, v169
	v_cvt_pk_bf16_f32 v224, v172, v173
	s_nop 1
	v_permlane32_swap_b32_e32 v220, v221
	v_cvt_pk_bf16_f32 v225, v174, v175
	v_permlane32_swap_b32_e32 v222, v224
	v_permlane32_swap_b32_e32 v164, v166
	v_permlane32_swap_b32_e32 v165, v167
	v_permlane32_swap_b32_e32 v176, v178
	v_permlane32_swap_b32_e32 v177, v179
	v_permlane32_swap_b32_e32 v228, v230
	v_permlane32_swap_b32_e32 v229, v231
	v_permlane32_swap_b32_e32 v223, v225
	s_branch .Lqsmb_join
.Lqsma_skip:
	v_exp_f32_e32 v177, v177
	v_exp_f32_e32 v179, v179
	v_exp_f32_e32 v166, v166
	v_exp_f32_e32 v167, v167
	v_exp_f32_e32 v165, v165
	v_exp_f32_e32 v102, v102
	v_exp_f32_e32 v196, v196
	v_exp_f32_e32 v197, v197
	v_exp_f32_e32 v228, v172
	v_exp_f32_e32 v215, v168
	v_add_f32_e32 v168, 0, v110
	v_add_f32_e32 v168, v164, v168
	v_add_f32_e32 v168, v108, v168
	v_add_f32_e32 v168, v111, v168
	v_add_f32_e32 v168, v107, v168
	v_add_f32_e32 v168, v109, v168
	v_add_f32_e32 v168, v105, v168
	v_add_f32_e32 v168, v106, v168
	v_add_f32_e32 v168, v101, v168
	v_add_f32_e32 v168, v104, v168
	v_add_f32_e32 v168, v100, v168
	v_add_f32_e32 v168, v103, v168
	v_exp_f32_e32 v212, v173
	v_add_f32_e32 v168, v97, v168
	v_exp_f32_e32 v213, v174
	v_add_f32_e32 v168, v99, v168
	v_exp_f32_e32 v214, v175
	v_add_f32_e32 v168, v96, v168
	v_add_f32_e32 v168, v98, v168
	v_add_f32_e32 v168, v212, v168
	v_add_f32_e32 v168, v213, v168
	v_add_f32_e32 v168, v214, v168
	v_add_f32_e32 v168, v177, v168
	v_exp_f32_e32 v225, v169
	v_add_f32_e32 v168, v179, v168
	v_exp_f32_e32 v226, v170
	v_add_f32_e32 v168, v166, v168
	v_exp_f32_e32 v227, v171
	v_add_f32_e32 v168, v167, v168
	v_add_f32_e32 v168, v215, v168
	v_add_f32_e32 v168, v225, v168
	v_add_f32_e32 v168, v226, v168
	v_add_f32_e32 v168, v227, v168
	v_add_f32_e32 v168, v228, v168
	v_add_f32_e32 v168, v165, v168
	v_add_f32_e32 v168, v102, v168
	v_add_f32_e32 v168, v196, v168
	v_add_f32_e32 v223, v197, v168
	v_mov_b32_e32 v224, v223
	v_cvt_pk_bf16_f32 v168, v110, v164
	v_cvt_pk_bf16_f32 v169, v108, v111
	v_cvt_pk_bf16_f32 v170, v107, v109
	s_nop 1
	v_permlane32_swap_b32_e32 v223, v224
	v_cvt_pk_bf16_f32 v171, v105, v106
	v_permlane32_swap_b32_e32 v168, v170
	v_cvt_pk_bf16_f32 v172, v101, v104
	v_cvt_pk_bf16_f32 v173, v100, v103
	v_cvt_pk_bf16_f32 v174, v97, v99
	v_cvt_pk_bf16_f32 v175, v96, v98
	v_cvt_pk_bf16_f32 v212, v212, v213
	v_cvt_pk_bf16_f32 v213, v214, v177
	v_cvt_pk_bf16_f32 v214, v179, v166
	v_cvt_pk_bf16_f32 v215, v167, v215
	v_cvt_pk_bf16_f32 v226, v225, v226
	v_cvt_pk_bf16_f32 v227, v227, v228
	v_cvt_pk_bf16_f32 v228, v165, v102
	v_cvt_pk_bf16_f32 v229, v196, v197
	v_permlane32_swap_b32_e32 v169, v171
	v_permlane32_swap_b32_e32 v172, v174
	v_permlane32_swap_b32_e32 v173, v175
	v_permlane32_swap_b32_e32 v212, v214
	v_permlane32_swap_b32_e32 v213, v215
	v_permlane32_swap_b32_e32 v226, v228
	v_permlane32_swap_b32_e32 v227, v229
	s_branch .Lqsma_join
; template <bool BAND> DI void partialSM(f32x16& p0, f32x16& p1, float& m_reg, float& mn, float& alpha, bool masked, const LAS float* tb, float C) {
;     ...
;   float pmax = p0[0];
; #pragma unroll
;   for (int r = 1; r < 16; ++r) pmax = fmaxf(pmax, p0[r]);
; #pragma unroll
;   for (int r = 0; r < 16; ++r) pmax = fmaxf(pmax, p1[r]);
;   { auto rr = __builtin_amdgcn_permlane32_swap(__float_as_uint(pmax), __float_as_uint(pmax), false, false);
;     pmax = fmaxf(__uint_as_float(rr[0]), __uint_as_float(rr[1])); }
;   if (__builtin_expect(__all(pmax - m_reg <= THRP), 1)) { mn = m_reg; alpha = 1.f; }
;   else { mn = fmaxf(m_reg, pmax); alpha = __builtin_amdgcn_exp2f((m_reg - mn) * CC); m_reg = mn; }
.Lpvmb_skip:
	s_nop 0
	s_nop 0
	s_cmp_gt_i32 s34, s37
	s_cselect_b64 s[16:17], -1, 0
	s_cmp_gt_i32 s37, s21
	s_cselect_b64 s[22:23], -1, 0
	s_or_b64 vcc, s[16:17], s[22:23]
	v_cndmask_b32_e32 v74, v74, v211, vcc
	v_cndmask_b32_e32 v75, v75, v211, vcc
	v_cndmask_b32_e32 v72, v104, v211, vcc
	v_cndmask_b32_e32 v73, v105, v211, vcc
	v_cndmask_b32_e32 v104, v102, v211, vcc
	v_cndmask_b32_e32 v102, v103, v211, vcc
	v_max_f32_e32 v103, v75, v75
	v_max_f32_e32 v105, v74, v74
	v_cndmask_b32_e32 v76, v76, v211, vcc
	v_cndmask_b32_e32 v77, v77, v211, vcc
	v_max_f32_e32 v103, v105, v103
	v_cndmask_b32_e32 v78, v78, v211, vcc
	v_cndmask_b32_e32 v79, v79, v211, vcc
	v_max3_f32 v103, v103, v76, v77
	v_cndmask_b32_e32 v80, v80, v211, vcc
	v_cndmask_b32_e32 v81, v81, v211, vcc
	v_max3_f32 v103, v103, v78, v79
	v_cndmask_b32_e32 v82, v82, v211, vcc
	v_cndmask_b32_e32 v83, v83, v211, vcc
	v_max3_f32 v103, v103, v80, v81
	v_cndmask_b32_e32 v84, v84, v211, vcc
	v_cndmask_b32_e32 v85, v85, v211, vcc
	v_max3_f32 v103, v103, v82, v83
	v_cndmask_b32_e32 v86, v86, v211, vcc
	v_cndmask_b32_e32 v87, v87, v211, vcc
	v_max3_f32 v103, v103, v84, v85
	v_cndmask_b32_e32 v88, v88, v211, vcc
	v_cndmask_b32_e32 v89, v89, v211, vcc
	v_max3_f32 v103, v103, v86, v87
	v_cndmask_b32_e32 v90, v90, v211, vcc
	v_cndmask_b32_e32 v91, v91, v211, vcc
	v_max3_f32 v103, v103, v88, v89
	v_cndmask_b32_e32 v92, v92, v211, vcc
	v_cndmask_b32_e32 v93, v93, v211, vcc
	v_max3_f32 v103, v103, v90, v91
	v_cndmask_b32_e32 v94, v94, v211, vcc
	v_cndmask_b32_e32 v95, v95, v211, vcc
	v_max3_f32 v103, v103, v92, v93
	v_cndmask_b32_e32 v96, v96, v211, vcc
	v_cndmask_b32_e32 v97, v97, v211, vcc
	v_max3_f32 v103, v103, v94, v95
	v_cndmask_b32_e32 v98, v98, v211, vcc
	v_cndmask_b32_e32 v99, v99, v211, vcc
	v_max3_f32 v103, v103, v96, v97
	v_cndmask_b32_e32 v100, v100, v211, vcc
	v_cndmask_b32_e32 v101, v101, v211, vcc
	v_max3_f32 v103, v103, v98, v99
	v_max3_f32 v103, v103, v100, v101
	v_max3_f32 v103, v103, v104, v102
	v_max3_f32 v103, v103, v72, v73
	v_mov_b32_e32 v105, v103
	s_nop 1
	v_permlane32_swap_b32_e32 v103, v105
	v_max_f32_e32 v105, v105, v105
	v_max_f32_e32 v103, v103, v103
	v_max_f32_e32 v103, v103, v105
	v_sub_f32_e32 v105, v103, v203
	v_cmp_ge_f32_e32 vcc, s84, v105
	v_mov_b32_e32 v222, 1.0
	s_cmp_eq_u64 vcc, exec
	s_branch .Lpvmb_join
.Lpvma_skip:
	s_nop 0
	s_cmp_gt_i32 s34, s39
	s_cselect_b64 s[16:17], -1, 0
	s_cmp_ge_i32 s37, s21
	s_cselect_b64 s[22:23], -1, 0
	s_or_b64 vcc, s[16:17], s[22:23]
	v_cndmask_b32_e32 v65, v65, v211, vcc
	v_cndmask_b32_e32 v64, v64, v211, vcc
	v_max_f32_e32 v168, v65, v65
	v_max_f32_e32 v169, v64, v64
	v_cndmask_b32_e32 v67, v67, v211, vcc
	v_cndmask_b32_e32 v66, v66, v211, vcc
	v_max_f32_e32 v168, v169, v168
	v_cndmask_b32_e32 v69, v69, v211, vcc
	v_cndmask_b32_e32 v68, v68, v211, vcc
	v_max3_f32 v168, v168, v66, v67
	v_cndmask_b32_e32 v71, v71, v211, vcc
	v_cndmask_b32_e32 v70, v70, v211, vcc
	v_max3_f32 v168, v168, v68, v69
	v_cndmask_b32_e32 v73, v73, v211, vcc
	v_cndmask_b32_e32 v72, v72, v211, vcc
	v_max3_f32 v168, v168, v70, v71
	v_cndmask_b32_e32 v75, v75, v211, vcc
	v_cndmask_b32_e32 v74, v74, v211, vcc
	v_max3_f32 v168, v168, v72, v73
	v_cndmask_b32_e32 v77, v77, v211, vcc
	v_cndmask_b32_e32 v76, v76, v211, vcc
	v_max3_f32 v168, v168, v74, v75
	v_cndmask_b32_e32 v79, v79, v211, vcc
	v_cndmask_b32_e32 v78, v78, v211, vcc
	v_max3_f32 v168, v168, v76, v77
	v_cndmask_b32_e32 v81, v81, v211, vcc
	v_cndmask_b32_e32 v80, v80, v211, vcc
	v_max3_f32 v168, v168, v78, v79
	v_cndmask_b32_e32 v83, v83, v211, vcc
	v_cndmask_b32_e32 v82, v82, v211, vcc
	v_max3_f32 v168, v168, v80, v81
	v_cndmask_b32_e32 v85, v85, v211, vcc
	v_cndmask_b32_e32 v84, v84, v211, vcc
	v_max3_f32 v168, v168, v82, v83
	v_cndmask_b32_e32 v87, v87, v211, vcc
	v_cndmask_b32_e32 v86, v86, v211, vcc
	v_max3_f32 v168, v168, v84, v85
	v_cndmask_b32_e32 v89, v89, v211, vcc
	v_cndmask_b32_e32 v88, v88, v211, vcc
	v_max3_f32 v168, v168, v86, v87
	v_cndmask_b32_e32 v91, v91, v211, vcc
	v_cndmask_b32_e32 v90, v90, v211, vcc
	v_max3_f32 v168, v168, v88, v89
	v_cndmask_b32_e32 v93, v93, v211, vcc
	v_cndmask_b32_e32 v92, v92, v211, vcc
	v_max3_f32 v168, v168, v90, v91
	v_cndmask_b32_e32 v95, v95, v211, vcc
	v_cndmask_b32_e32 v94, v94, v211, vcc
	v_max3_f32 v168, v168, v92, v93
	v_max3_f32 v168, v168, v94, v95
	v_mov_b32_e32 v169, v168
	s_nop 1
	v_permlane32_swap_b32_e32 v168, v169
	v_max_f32_e32 v169, v169, v169
	v_max_f32_e32 v168, v168, v168
	v_max_f32_e32 v168, v168, v169
	v_sub_f32_e32 v169, v168, v203
	v_cmp_ge_f32_e32 vcc, s84, v169
	v_mov_b32_e32 v177, 1.0
	s_cmp_eq_u64 vcc, exec
	s_branch .Lpvma_join
